# v25 variant: hyconv row touch issued one Stockham step earlier (start of the middle step)
# baseline (speedup 1.0000x reference)
.LBB0_438:
	s_or_b64 exec, exec, s[0:1]
	v_mov_b32_e32 v47, v32
	s_waitcnt lgkmcnt(0)
	s_barrier
	v_lshl_add_u64 v[224:225], v[78:79], 0, v[172:173]
	s_mov_b64 s[100:101], 0x40000
	v_lshl_add_u64 v[228:229], v[224:225], 0, s[100:101]
	global_load_dword v226, v[228:229], off
	s_mov_b64 s[100:101], 0x100000
	v_lshl_add_u64 v[228:229], v[224:225], 0, s[100:101]
	global_load_dword v226, v[228:229], off
	s_mov_b32 s11, s14
	v_and_b32_e32 v81, 31, v47
	v_cvt_f32_ubyte0_e32 v24, v81
	v_mul_f32_e32 v110, 0x3b000000, v24
	v_sin_f32_e32 v24, v110
	v_ashrrev_i32_e32 v0, 4, v47
	v_lshlrev_b32_e32 v0, 3, v0
	v_lshlrev_b32_e32 v1, 3, v47
	v_cos_f32_e32 v110, v110
	v_add3_u32 v25, 0, v0, v1
	ds_read_b64 v[0:1], v25
	ds_read_b64 v[2:3], v25 offset:4352
	ds_read_b64 v[4:5], v25 offset:8704
	ds_read_b64 v[6:7], v25 offset:13056
	ds_read_b64 v[8:9], v25 offset:17408
	ds_read_b64 v[10:11], v25 offset:21760
	ds_read_b64 v[12:13], v25 offset:26112
	ds_read_b64 v[14:15], v25 offset:30464
	ds_read_b64 v[16:17], v25 offset:34816
	ds_read_b64 v[18:19], v25 offset:39168
	ds_read_b64 v[20:21], v25 offset:43520
	ds_read_b64 v[22:23], v25 offset:47872
	v_xor_b32_e32 v111, 0x80000000, v24
	s_waitcnt lgkmcnt(10)
	v_pk_mul_f32 v[118:119], v[2:3], v[24:25] op_sel:[1,0] op_sel_hi:[0,0] neg_hi:[0,1]
	v_pk_fma_f32 v[2:3], v[2:3], v[110:111], v[118:119] op_sel_hi:[1,0,1]
	v_pk_mul_f32 v[118:119], v[24:25], v[110:111] op_sel:[0,1] op_sel_hi:[0,0] neg_hi:[1,0]
	v_pk_fma_f32 v[118:119], v[110:111], v[110:111], v[118:119] op_sel_hi:[0,1,1]
	ds_read_b64 v[26:27], v25 offset:52224
	ds_read_b64 v[28:29], v25 offset:56576
	ds_read_b64 v[30:31], v25 offset:60928
	ds_read_b64 v[102:103], v25 offset:65280
	s_waitcnt lgkmcnt(13)
	v_pk_mul_f32 v[120:121], v[4:5], v[118:119] op_sel:[1,1] op_sel_hi:[0,1] neg_lo:[0,1]
	v_pk_fma_f32 v[4:5], v[4:5], v[118:119], v[120:121] op_sel_hi:[1,0,1]
	v_pk_mul_f32 v[120:121], v[24:25], v[118:119] op_sel:[0,1] op_sel_hi:[0,0] neg_hi:[1,0]
	v_pk_fma_f32 v[118:119], v[110:111], v[118:119], v[120:121] op_sel_hi:[0,1,1]
	s_mov_b32 s35, s30
	s_waitcnt lgkmcnt(12)
	v_pk_mul_f32 v[120:121], v[6:7], v[118:119] op_sel:[1,1] op_sel_hi:[0,1] neg_lo:[0,1]
	v_pk_fma_f32 v[6:7], v[6:7], v[118:119], v[120:121] op_sel_hi:[1,0,1]
	v_pk_mul_f32 v[120:121], v[24:25], v[118:119] op_sel:[0,1] op_sel_hi:[0,0] neg_hi:[1,0]
	v_pk_fma_f32 v[118:119], v[110:111], v[118:119], v[120:121] op_sel_hi:[0,1,1]
	s_mov_b32 s0, s19
	s_waitcnt lgkmcnt(11)
	v_pk_mul_f32 v[120:121], v[8:9], v[118:119] op_sel:[1,1] op_sel_hi:[0,1] neg_lo:[0,1]
	v_pk_fma_f32 v[8:9], v[8:9], v[118:119], v[120:121] op_sel_hi:[1,0,1]
	v_pk_mul_f32 v[120:121], v[24:25], v[118:119] op_sel:[0,1] op_sel_hi:[0,0] neg_hi:[1,0]
	v_pk_fma_f32 v[118:119], v[110:111], v[118:119], v[120:121] op_sel_hi:[0,1,1]
	s_waitcnt lgkmcnt(0)
	v_pk_mul_f32 v[120:121], v[10:11], v[118:119] op_sel:[1,1] op_sel_hi:[0,1] neg_lo:[0,1]
	v_pk_fma_f32 v[10:11], v[10:11], v[118:119], v[120:121] op_sel_hi:[1,0,1]
	v_pk_mul_f32 v[120:121], v[24:25], v[118:119] op_sel:[0,1] op_sel_hi:[0,0] neg_hi:[1,0]
	v_pk_fma_f32 v[118:119], v[110:111], v[118:119], v[120:121] op_sel_hi:[0,1,1]
	s_barrier
	v_pk_mul_f32 v[120:121], v[12:13], v[118:119] op_sel:[1,1] op_sel_hi:[0,1] neg_lo:[0,1]
	v_pk_fma_f32 v[12:13], v[12:13], v[118:119], v[120:121] op_sel_hi:[1,0,1]
	v_pk_mul_f32 v[120:121], v[24:25], v[118:119] op_sel:[0,1] op_sel_hi:[0,0] neg_hi:[1,0]
	v_pk_fma_f32 v[118:119], v[110:111], v[118:119], v[120:121] op_sel_hi:[0,1,1]
	s_nop 0
	v_pk_mul_f32 v[120:121], v[14:15], v[118:119] op_sel:[1,1] op_sel_hi:[0,1] neg_lo:[0,1]
	v_pk_fma_f32 v[14:15], v[14:15], v[118:119], v[120:121] op_sel_hi:[1,0,1]
	v_pk_mul_f32 v[120:121], v[24:25], v[118:119] op_sel:[0,1] op_sel_hi:[0,0] neg_hi:[1,0]
	v_pk_fma_f32 v[118:119], v[110:111], v[118:119], v[120:121] op_sel_hi:[0,1,1]
	s_nop 0
	v_pk_mul_f32 v[120:121], v[16:17], v[118:119] op_sel:[1,1] op_sel_hi:[0,1] neg_lo:[0,1]
	v_pk_fma_f32 v[16:17], v[16:17], v[118:119], v[120:121] op_sel_hi:[1,0,1]
	v_pk_mul_f32 v[120:121], v[24:25], v[118:119] op_sel:[0,1] op_sel_hi:[0,0] neg_hi:[1,0]
	v_pk_fma_f32 v[118:119], v[110:111], v[118:119], v[120:121] op_sel_hi:[0,1,1]
	s_nop 0
	v_pk_mul_f32 v[120:121], v[18:19], v[118:119] op_sel:[1,1] op_sel_hi:[0,1] neg_lo:[0,1]
	v_pk_fma_f32 v[18:19], v[18:19], v[118:119], v[120:121] op_sel_hi:[1,0,1]
	v_pk_mul_f32 v[120:121], v[24:25], v[118:119] op_sel:[0,1] op_sel_hi:[0,0] neg_hi:[1,0]
	v_pk_fma_f32 v[118:119], v[110:111], v[118:119], v[120:121] op_sel_hi:[0,1,1]
	s_nop 0
	v_pk_mul_f32 v[120:121], v[20:21], v[118:119] op_sel:[1,1] op_sel_hi:[0,1] neg_lo:[0,1]
	v_pk_fma_f32 v[20:21], v[20:21], v[118:119], v[120:121] op_sel_hi:[1,0,1]
	v_pk_mul_f32 v[120:121], v[24:25], v[118:119] op_sel:[0,1] op_sel_hi:[0,0] neg_hi:[1,0]
	v_pk_fma_f32 v[118:119], v[110:111], v[118:119], v[120:121] op_sel_hi:[0,1,1]
	s_nop 0
	v_pk_mul_f32 v[120:121], v[22:23], v[118:119] op_sel:[1,1] op_sel_hi:[0,1] neg_lo:[0,1]
	v_pk_fma_f32 v[22:23], v[22:23], v[118:119], v[120:121] op_sel_hi:[1,0,1]
	v_pk_mul_f32 v[120:121], v[24:25], v[118:119] op_sel:[0,1] op_sel_hi:[0,0] neg_hi:[1,0]
	v_pk_fma_f32 v[118:119], v[110:111], v[118:119], v[120:121] op_sel_hi:[0,1,1]
	s_nop 0
	v_pk_mul_f32 v[120:121], v[26:27], v[118:119] op_sel:[1,1] op_sel_hi:[0,1] neg_lo:[0,1]
	v_pk_fma_f32 v[26:27], v[26:27], v[118:119], v[120:121] op_sel_hi:[1,0,1]
	v_pk_mul_f32 v[120:121], v[24:25], v[118:119] op_sel:[0,1] op_sel_hi:[0,0] neg_hi:[1,0]
	v_pk_fma_f32 v[118:119], v[110:111], v[118:119], v[120:121] op_sel_hi:[0,1,1]
	s_nop 0
	v_pk_mul_f32 v[120:121], v[28:29], v[118:119] op_sel:[1,1] op_sel_hi:[0,1] neg_lo:[0,1]
	v_pk_fma_f32 v[28:29], v[28:29], v[118:119], v[120:121] op_sel_hi:[1,0,1]
	v_pk_mul_f32 v[120:121], v[24:25], v[118:119] op_sel:[0,1] op_sel_hi:[0,0] neg_hi:[1,0]
	v_pk_fma_f32 v[118:119], v[110:111], v[118:119], v[120:121] op_sel_hi:[0,1,1]
	v_pk_mul_f32 v[24:25], v[24:25], v[118:119] op_sel:[0,1] op_sel_hi:[0,0] neg_hi:[1,0]
	v_pk_fma_f32 v[24:25], v[110:111], v[118:119], v[24:25] op_sel_hi:[0,1,1]
	v_pk_mul_f32 v[110:111], v[102:103], v[24:25] op_sel:[1,1] op_sel_hi:[0,1] neg_lo:[0,1]
	v_pk_fma_f32 v[24:25], v[102:103], v[24:25], v[110:111] op_sel_hi:[1,0,1]
	v_pk_add_f32 v[102:103], v[0:1], v[16:17]
	v_pk_add_f32 v[0:1], v[0:1], v[16:17] neg_lo:[0,1] neg_hi:[0,1]
	v_pk_add_f32 v[16:17], v[2:3], v[18:19]
	v_pk_add_f32 v[2:3], v[2:3], v[18:19] neg_lo:[0,1] neg_hi:[0,1]
	v_pk_mul_f32 v[120:121], v[30:31], v[118:119] op_sel:[1,1] op_sel_hi:[0,1] neg_lo:[0,1]
	v_pk_mul_f32 v[18:19], v[2:3], s[18:19]
	v_pk_fma_f32 v[30:31], v[30:31], v[118:119], v[120:121] op_sel_hi:[1,0,1]
	v_pk_fma_f32 v[2:3], v[2:3], s[30:31], v[18:19] op_sel:[0,0,1] op_sel_hi:[1,0,0]
	v_pk_add_f32 v[18:19], v[4:5], v[20:21]
	v_pk_add_f32 v[4:5], v[4:5], v[20:21] neg_lo:[0,1] neg_hi:[0,1]
	s_nop 0
	v_pk_mul_f32 v[20:21], v[4:5], s[10:11]
	s_nop 0
	v_pk_fma_f32 v[4:5], v[4:5], s[14:15], v[20:21] op_sel:[0,0,1] op_sel_hi:[1,0,0]
	v_pk_add_f32 v[20:21], v[6:7], v[22:23]
	v_pk_add_f32 v[6:7], v[6:7], v[22:23] neg_lo:[0,1] neg_hi:[0,1]
	s_nop 0
	v_pk_mul_f32 v[22:23], v[6:7], s[34:35]
	s_nop 0
	v_pk_fma_f32 v[6:7], v[6:7], s[0:1], v[22:23] op_sel:[0,0,1] op_sel_hi:[1,0,0]
	v_pk_add_f32 v[22:23], v[8:9], v[26:27]
	v_pk_add_f32 v[8:9], v[8:9], v[26:27] neg_lo:[0,1] neg_hi:[0,1]
	v_pk_add_f32 v[26:27], v[10:11], v[28:29]
	v_pk_add_f32 v[10:11], v[10:11], v[28:29] neg_lo:[0,1] neg_hi:[0,1]
	s_nop 0
	v_pk_mul_f32 v[28:29], v[10:11], s[34:35]
	s_nop 0
	v_pk_fma_f32 v[10:11], v[10:11], s[0:1], v[28:29] op_sel:[0,0,1] op_sel_hi:[1,0,0] neg_lo:[1,0,0] neg_hi:[1,0,0]
	v_pk_add_f32 v[28:29], v[12:13], v[30:31]
	v_pk_add_f32 v[12:13], v[12:13], v[30:31] neg_lo:[0,1] neg_hi:[0,1]
	s_nop 0
	v_pk_mul_f32 v[30:31], v[12:13], s[10:11]
	s_nop 0
	v_pk_fma_f32 v[12:13], v[12:13], s[14:15], v[30:31] op_sel:[0,0,1] op_sel_hi:[1,0,0] neg_lo:[1,0,0] neg_hi:[1,0,0]
	v_pk_add_f32 v[30:31], v[14:15], v[24:25]
	v_pk_add_f32 v[14:15], v[14:15], v[24:25] neg_lo:[0,1] neg_hi:[0,1]
	s_nop 0
	v_pk_mul_f32 v[24:25], v[14:15], s[18:19]
	s_nop 0
	v_pk_fma_f32 v[14:15], v[14:15], s[30:31], v[24:25] op_sel:[0,0,1] op_sel_hi:[1,0,0] neg_lo:[1,0,0] neg_hi:[1,0,0]
	v_pk_add_f32 v[24:25], v[102:103], v[22:23]
	v_pk_add_f32 v[22:23], v[102:103], v[22:23] neg_lo:[0,1] neg_hi:[0,1]
	v_pk_add_f32 v[102:103], v[16:17], v[26:27]
	v_pk_add_f32 v[16:17], v[16:17], v[26:27] neg_lo:[0,1] neg_hi:[0,1]
	s_nop 0
	v_pk_mul_f32 v[26:27], v[16:17], s[10:11]
	s_nop 0
	v_pk_fma_f32 v[16:17], v[16:17], s[14:15], v[26:27] op_sel:[0,0,1] op_sel_hi:[1,0,0]
	v_pk_add_f32 v[26:27], v[18:19], v[28:29]
	v_pk_add_f32 v[18:19], v[18:19], v[28:29] neg_lo:[0,1] neg_hi:[0,1]
	v_pk_add_f32 v[28:29], v[20:21], v[30:31]
	v_pk_add_f32 v[20:21], v[20:21], v[30:31] neg_lo:[0,1] neg_hi:[0,1]
	s_nop 0
	v_pk_mul_f32 v[30:31], v[20:21], s[10:11]
	s_nop 0
	v_pk_fma_f32 v[20:21], v[20:21], s[14:15], v[30:31] op_sel:[0,0,1] op_sel_hi:[1,0,0] neg_lo:[1,0,0] neg_hi:[1,0,0]
	v_pk_add_f32 v[30:31], v[0:1], v[8:9] op_sel:[0,1] op_sel_hi:[1,0] neg_hi:[0,1]
	v_pk_add_f32 v[0:1], v[0:1], v[8:9] op_sel:[0,1] op_sel_hi:[1,0] neg_lo:[0,1]
	v_pk_add_f32 v[8:9], v[2:3], v[10:11]
	v_pk_add_f32 v[2:3], v[2:3], v[10:11] neg_lo:[0,1] neg_hi:[0,1]
	s_nop 0
	v_pk_mul_f32 v[10:11], v[2:3], s[10:11]
	s_nop 0
	v_pk_fma_f32 v[2:3], v[2:3], s[14:15], v[10:11] op_sel:[0,0,1] op_sel_hi:[1,0,0]
	v_pk_add_f32 v[10:11], v[4:5], v[12:13]
	v_pk_add_f32 v[4:5], v[4:5], v[12:13] neg_lo:[0,1] neg_hi:[0,1]
	v_pk_add_f32 v[12:13], v[6:7], v[14:15]
	v_pk_add_f32 v[6:7], v[6:7], v[14:15] neg_lo:[0,1] neg_hi:[0,1]
	s_nop 0
	v_pk_mul_f32 v[14:15], v[6:7], s[10:11]
	s_nop 0
	v_pk_fma_f32 v[6:7], v[6:7], s[14:15], v[14:15] op_sel:[0,0,1] op_sel_hi:[1,0,0] neg_lo:[1,0,0] neg_hi:[1,0,0]
	v_pk_add_f32 v[14:15], v[24:25], v[26:27]
	v_pk_add_f32 v[24:25], v[24:25], v[26:27] neg_lo:[0,1] neg_hi:[0,1]
	v_pk_add_f32 v[26:27], v[102:103], v[28:29]
	v_pk_add_f32 v[28:29], v[102:103], v[28:29] neg_lo:[0,1] neg_hi:[0,1]
	v_pk_add_f32 v[102:103], v[22:23], v[18:19] op_sel:[0,1] op_sel_hi:[1,0] neg_hi:[0,1]
	v_pk_add_f32 v[18:19], v[22:23], v[18:19] op_sel:[0,1] op_sel_hi:[1,0] neg_lo:[0,1]
	v_pk_add_f32 v[22:23], v[16:17], v[20:21]
	v_pk_add_f32 v[16:17], v[16:17], v[20:21] neg_lo:[0,1] neg_hi:[0,1]
	v_pk_add_f32 v[20:21], v[30:31], v[10:11]
	v_pk_add_f32 v[10:11], v[30:31], v[10:11] neg_lo:[0,1] neg_hi:[0,1]
	v_pk_add_f32 v[30:31], v[8:9], v[12:13]
	v_pk_add_f32 v[8:9], v[8:9], v[12:13] neg_lo:[0,1] neg_hi:[0,1]
	v_pk_add_f32 v[12:13], v[0:1], v[4:5] op_sel:[0,1] op_sel_hi:[1,0] neg_hi:[0,1]
	v_pk_add_f32 v[0:1], v[0:1], v[4:5] op_sel:[0,1] op_sel_hi:[1,0] neg_lo:[0,1]
	v_pk_add_f32 v[4:5], v[2:3], v[6:7]
	v_pk_add_f32 v[2:3], v[2:3], v[6:7] neg_lo:[0,1] neg_hi:[0,1]
	s_nop 0
	v_pk_mul_f32 v[2:3], v[2:3], s[22:23]
	v_pk_add_f32 v[6:7], v[14:15], v[26:27]
	v_pk_add_f32 v[14:15], v[14:15], v[26:27] neg_lo:[0,1] neg_hi:[0,1]
	v_pk_add_f32 v[26:27], v[24:25], v[28:29] op_sel:[0,1] op_sel_hi:[1,0] neg_hi:[0,1]
	v_pk_add_f32 v[24:25], v[24:25], v[28:29] op_sel:[0,1] op_sel_hi:[1,0] neg_lo:[0,1]
	v_pk_add_f32 v[28:29], v[102:103], v[22:23]
	v_pk_add_f32 v[22:23], v[102:103], v[22:23] neg_lo:[0,1] neg_hi:[0,1]
	v_pk_add_f32 v[102:103], v[18:19], v[16:17] op_sel:[0,1] op_sel_hi:[1,0] neg_hi:[0,1]
	v_pk_add_f32 v[16:17], v[18:19], v[16:17] op_sel:[0,1] op_sel_hi:[1,0] neg_lo:[0,1]
	v_pk_add_f32 v[18:19], v[20:21], v[30:31]
	v_pk_add_f32 v[20:21], v[20:21], v[30:31] neg_lo:[0,1] neg_hi:[0,1]
	v_pk_add_f32 v[30:31], v[10:11], v[8:9] op_sel:[0,1] op_sel_hi:[1,0] neg_hi:[0,1]
	v_pk_add_f32 v[8:9], v[10:11], v[8:9] op_sel:[0,1] op_sel_hi:[1,0] neg_lo:[0,1]
	v_pk_add_f32 v[10:11], v[12:13], v[4:5]
	v_pk_add_f32 v[4:5], v[12:13], v[4:5] neg_lo:[0,1] neg_hi:[0,1]
	v_pk_add_f32 v[12:13], v[0:1], v[2:3] op_sel:[0,1] op_sel_hi:[1,0]
	v_pk_add_f32 v[0:1], v[0:1], v[2:3] op_sel:[0,1] op_sel_hi:[1,0] neg_lo:[0,1] neg_hi:[0,1]
	v_lshlrev_b32_e32 v2, 4, v47
	v_and_or_b32 v2, v2, s7, v81
	v_ashrrev_i32_e32 v3, 4, v2
	v_lshlrev_b32_e32 v3, 3, v3
	v_lshlrev_b32_e32 v2, 3, v2
	v_add3_u32 v2, 0, v3, v2
	v_add_u32_e32 v3, 0x800, v2
	v_mov_b32_e32 v47, v32
	ds_write2_b64 v2, v[6:7], v[18:19] offset1:34
	ds_write2_b64 v3, v[14:15], v[20:21] offset0:16 offset1:50
	ds_write2_b64 v2, v[26:27], v[30:31] offset0:136 offset1:170
	ds_write2_b64 v3, v[24:25], v[8:9] offset0:152 offset1:186
	ds_write2_b64 v2, v[28:29], v[10:11] offset0:68 offset1:102
	ds_write2_b64 v3, v[22:23], v[4:5] offset0:84 offset1:118
	ds_write2_b64 v2, v[102:103], v[12:13] offset0:204 offset1:238
	ds_write2_b64 v3, v[16:17], v[0:1] offset0:220 offset1:254
	s_waitcnt lgkmcnt(0)
	s_barrier
	s_nop 0
	v_and_b32_e32 v81, 0x1ff, v47
	v_cvt_f32_u32_e32 v24, v81
	v_ashrrev_i32_e32 v0, 4, v47
	v_lshlrev_b32_e32 v0, 3, v0
	v_lshlrev_b32_e32 v1, 3, v47
	v_mul_f32_e32 v110, 0x39000000, v24
	v_sin_f32_e32 v24, v110
	v_cos_f32_e32 v110, v110
	v_add3_u32 v25, 0, v0, v1
	ds_read_b64 v[0:1], v25
	ds_read_b64 v[2:3], v25 offset:4352
	ds_read_b64 v[4:5], v25 offset:8704
	ds_read_b64 v[6:7], v25 offset:13056
	ds_read_b64 v[8:9], v25 offset:17408
	ds_read_b64 v[10:11], v25 offset:21760
	ds_read_b64 v[12:13], v25 offset:26112
	ds_read_b64 v[14:15], v25 offset:30464
	v_xor_b32_e32 v111, 0x80000000, v24
	s_waitcnt lgkmcnt(6)
	v_pk_mul_f32 v[118:119], v[2:3], v[24:25] op_sel:[1,0] op_sel_hi:[0,0] neg_hi:[0,1]
	v_pk_fma_f32 v[2:3], v[2:3], v[110:111], v[118:119] op_sel_hi:[1,0,1]
	v_pk_mul_f32 v[118:119], v[24:25], v[110:111] op_sel:[0,1] op_sel_hi:[0,0] neg_hi:[1,0]
	v_pk_fma_f32 v[118:119], v[110:111], v[110:111], v[118:119] op_sel_hi:[0,1,1]
	ds_read_b64 v[16:17], v25 offset:34816
	ds_read_b64 v[18:19], v25 offset:39168
	ds_read_b64 v[20:21], v25 offset:43520
	ds_read_b64 v[22:23], v25 offset:47872
	s_waitcnt lgkmcnt(9)
	v_pk_mul_f32 v[120:121], v[4:5], v[118:119] op_sel:[1,1] op_sel_hi:[0,1] neg_lo:[0,1]
	v_pk_fma_f32 v[4:5], v[4:5], v[118:119], v[120:121] op_sel_hi:[1,0,1]
	v_pk_mul_f32 v[120:121], v[24:25], v[118:119] op_sel:[0,1] op_sel_hi:[0,0] neg_hi:[1,0]
	v_pk_fma_f32 v[118:119], v[110:111], v[118:119], v[120:121] op_sel_hi:[0,1,1]
	ds_read_b64 v[26:27], v25 offset:52224
	ds_read_b64 v[28:29], v25 offset:56576
	ds_read_b64 v[30:31], v25 offset:60928
	ds_read_b64 v[102:103], v25 offset:65280
	s_waitcnt lgkmcnt(12)
	v_pk_mul_f32 v[120:121], v[6:7], v[118:119] op_sel:[1,1] op_sel_hi:[0,1] neg_lo:[0,1]
	v_pk_fma_f32 v[6:7], v[6:7], v[118:119], v[120:121] op_sel_hi:[1,0,1]
	v_pk_mul_f32 v[120:121], v[24:25], v[118:119] op_sel:[0,1] op_sel_hi:[0,0] neg_hi:[1,0]
	v_pk_fma_f32 v[118:119], v[110:111], v[118:119], v[120:121] op_sel_hi:[0,1,1]
	s_waitcnt lgkmcnt(0)
	v_pk_mul_f32 v[120:121], v[8:9], v[118:119] op_sel:[1,1] op_sel_hi:[0,1] neg_lo:[0,1]
	v_pk_fma_f32 v[8:9], v[8:9], v[118:119], v[120:121] op_sel_hi:[1,0,1]
	v_pk_mul_f32 v[120:121], v[24:25], v[118:119] op_sel:[0,1] op_sel_hi:[0,0] neg_hi:[1,0]
	v_pk_fma_f32 v[118:119], v[110:111], v[118:119], v[120:121] op_sel_hi:[0,1,1]
	s_barrier
	v_pk_mul_f32 v[120:121], v[10:11], v[118:119] op_sel:[1,1] op_sel_hi:[0,1] neg_lo:[0,1]
	v_pk_fma_f32 v[10:11], v[10:11], v[118:119], v[120:121] op_sel_hi:[1,0,1]
	v_pk_mul_f32 v[120:121], v[24:25], v[118:119] op_sel:[0,1] op_sel_hi:[0,0] neg_hi:[1,0]
	v_pk_fma_f32 v[118:119], v[110:111], v[118:119], v[120:121] op_sel_hi:[0,1,1]
	s_nop 0
	v_pk_mul_f32 v[120:121], v[12:13], v[118:119] op_sel:[1,1] op_sel_hi:[0,1] neg_lo:[0,1]
	v_pk_fma_f32 v[12:13], v[12:13], v[118:119], v[120:121] op_sel_hi:[1,0,1]
	v_pk_mul_f32 v[120:121], v[24:25], v[118:119] op_sel:[0,1] op_sel_hi:[0,0] neg_hi:[1,0]
	v_pk_fma_f32 v[118:119], v[110:111], v[118:119], v[120:121] op_sel_hi:[0,1,1]
	s_nop 0
	v_pk_mul_f32 v[120:121], v[14:15], v[118:119] op_sel:[1,1] op_sel_hi:[0,1] neg_lo:[0,1]
	v_pk_fma_f32 v[14:15], v[14:15], v[118:119], v[120:121] op_sel_hi:[1,0,1]
	v_pk_mul_f32 v[120:121], v[24:25], v[118:119] op_sel:[0,1] op_sel_hi:[0,0] neg_hi:[1,0]
	v_pk_fma_f32 v[118:119], v[110:111], v[118:119], v[120:121] op_sel_hi:[0,1,1]
	s_nop 0
	v_pk_mul_f32 v[120:121], v[16:17], v[118:119] op_sel:[1,1] op_sel_hi:[0,1] neg_lo:[0,1]
	v_pk_fma_f32 v[16:17], v[16:17], v[118:119], v[120:121] op_sel_hi:[1,0,1]
	v_pk_mul_f32 v[120:121], v[24:25], v[118:119] op_sel:[0,1] op_sel_hi:[0,0] neg_hi:[1,0]
	v_pk_fma_f32 v[118:119], v[110:111], v[118:119], v[120:121] op_sel_hi:[0,1,1]
	s_nop 0
	v_pk_mul_f32 v[120:121], v[18:19], v[118:119] op_sel:[1,1] op_sel_hi:[0,1] neg_lo:[0,1]
	v_pk_fma_f32 v[18:19], v[18:19], v[118:119], v[120:121] op_sel_hi:[1,0,1]
	v_pk_mul_f32 v[120:121], v[24:25], v[118:119] op_sel:[0,1] op_sel_hi:[0,0] neg_hi:[1,0]
	v_pk_fma_f32 v[118:119], v[110:111], v[118:119], v[120:121] op_sel_hi:[0,1,1]
	s_nop 0
	v_pk_mul_f32 v[120:121], v[20:21], v[118:119] op_sel:[1,1] op_sel_hi:[0,1] neg_lo:[0,1]
	v_pk_fma_f32 v[20:21], v[20:21], v[118:119], v[120:121] op_sel_hi:[1,0,1]
	v_pk_mul_f32 v[120:121], v[24:25], v[118:119] op_sel:[0,1] op_sel_hi:[0,0] neg_hi:[1,0]
	v_pk_fma_f32 v[118:119], v[110:111], v[118:119], v[120:121] op_sel_hi:[0,1,1]
	s_nop 0
	v_pk_mul_f32 v[120:121], v[22:23], v[118:119] op_sel:[1,1] op_sel_hi:[0,1] neg_lo:[0,1]
	v_pk_fma_f32 v[22:23], v[22:23], v[118:119], v[120:121] op_sel_hi:[1,0,1]
	v_pk_mul_f32 v[120:121], v[24:25], v[118:119] op_sel:[0,1] op_sel_hi:[0,0] neg_hi:[1,0]
	v_pk_fma_f32 v[118:119], v[110:111], v[118:119], v[120:121] op_sel_hi:[0,1,1]
	s_nop 0
	v_pk_mul_f32 v[120:121], v[26:27], v[118:119] op_sel:[1,1] op_sel_hi:[0,1] neg_lo:[0,1]
	v_pk_fma_f32 v[26:27], v[26:27], v[118:119], v[120:121] op_sel_hi:[1,0,1]
	v_pk_mul_f32 v[120:121], v[24:25], v[118:119] op_sel:[0,1] op_sel_hi:[0,0] neg_hi:[1,0]
	v_pk_fma_f32 v[118:119], v[110:111], v[118:119], v[120:121] op_sel_hi:[0,1,1]
	s_nop 0
	v_pk_mul_f32 v[120:121], v[28:29], v[118:119] op_sel:[1,1] op_sel_hi:[0,1] neg_lo:[0,1]
	v_pk_fma_f32 v[28:29], v[28:29], v[118:119], v[120:121] op_sel_hi:[1,0,1]
	v_pk_mul_f32 v[120:121], v[24:25], v[118:119] op_sel:[0,1] op_sel_hi:[0,0] neg_hi:[1,0]
	v_pk_fma_f32 v[118:119], v[110:111], v[118:119], v[120:121] op_sel_hi:[0,1,1]
	v_pk_mul_f32 v[24:25], v[24:25], v[118:119] op_sel:[0,1] op_sel_hi:[0,0] neg_hi:[1,0]
	v_pk_fma_f32 v[24:25], v[110:111], v[118:119], v[24:25] op_sel_hi:[0,1,1]
	v_pk_mul_f32 v[110:111], v[102:103], v[24:25] op_sel:[1,1] op_sel_hi:[0,1] neg_lo:[0,1]
	v_pk_fma_f32 v[24:25], v[102:103], v[24:25], v[110:111] op_sel_hi:[1,0,1]
	v_pk_add_f32 v[102:103], v[0:1], v[16:17]
	v_pk_add_f32 v[0:1], v[0:1], v[16:17] neg_lo:[0,1] neg_hi:[0,1]
	v_pk_add_f32 v[16:17], v[2:3], v[18:19]
	v_pk_add_f32 v[2:3], v[2:3], v[18:19] neg_lo:[0,1] neg_hi:[0,1]
	v_pk_mul_f32 v[120:121], v[30:31], v[118:119] op_sel:[1,1] op_sel_hi:[0,1] neg_lo:[0,1]
	v_pk_mul_f32 v[18:19], v[2:3], s[18:19]
	v_pk_fma_f32 v[30:31], v[30:31], v[118:119], v[120:121] op_sel_hi:[1,0,1]
	v_pk_fma_f32 v[2:3], v[2:3], s[30:31], v[18:19] op_sel:[0,0,1] op_sel_hi:[1,0,0]
	v_pk_add_f32 v[18:19], v[4:5], v[20:21]
	v_pk_add_f32 v[4:5], v[4:5], v[20:21] neg_lo:[0,1] neg_hi:[0,1]
	s_nop 0
	v_pk_mul_f32 v[20:21], v[4:5], s[10:11]
	s_nop 0
	v_pk_fma_f32 v[4:5], v[4:5], s[14:15], v[20:21] op_sel:[0,0,1] op_sel_hi:[1,0,0]
	v_pk_add_f32 v[20:21], v[6:7], v[22:23]
	v_pk_add_f32 v[6:7], v[6:7], v[22:23] neg_lo:[0,1] neg_hi:[0,1]
	s_nop 0
	v_pk_mul_f32 v[22:23], v[6:7], s[34:35]
	s_nop 0
	v_pk_fma_f32 v[6:7], v[6:7], s[0:1], v[22:23] op_sel:[0,0,1] op_sel_hi:[1,0,0]
	v_pk_add_f32 v[22:23], v[8:9], v[26:27]
	v_pk_add_f32 v[8:9], v[8:9], v[26:27] neg_lo:[0,1] neg_hi:[0,1]
	v_pk_add_f32 v[26:27], v[10:11], v[28:29]
	v_pk_add_f32 v[10:11], v[10:11], v[28:29] neg_lo:[0,1] neg_hi:[0,1]
	s_nop 0
	v_pk_mul_f32 v[28:29], v[10:11], s[34:35]
	s_nop 0
	v_pk_fma_f32 v[10:11], v[10:11], s[0:1], v[28:29] op_sel:[0,0,1] op_sel_hi:[1,0,0] neg_lo:[1,0,0] neg_hi:[1,0,0]
	v_pk_add_f32 v[28:29], v[12:13], v[30:31]
	v_pk_add_f32 v[12:13], v[12:13], v[30:31] neg_lo:[0,1] neg_hi:[0,1]
	s_nop 0
	v_pk_mul_f32 v[30:31], v[12:13], s[10:11]
	s_nop 0
	v_pk_fma_f32 v[12:13], v[12:13], s[14:15], v[30:31] op_sel:[0,0,1] op_sel_hi:[1,0,0] neg_lo:[1,0,0] neg_hi:[1,0,0]
	v_pk_add_f32 v[30:31], v[14:15], v[24:25]
	v_pk_add_f32 v[14:15], v[14:15], v[24:25] neg_lo:[0,1] neg_hi:[0,1]
	s_nop 0
	v_pk_mul_f32 v[24:25], v[14:15], s[18:19]
	s_nop 0
	v_pk_fma_f32 v[14:15], v[14:15], s[30:31], v[24:25] op_sel:[0,0,1] op_sel_hi:[1,0,0] neg_lo:[1,0,0] neg_hi:[1,0,0]
	v_pk_add_f32 v[24:25], v[102:103], v[22:23]
	v_pk_add_f32 v[22:23], v[102:103], v[22:23] neg_lo:[0,1] neg_hi:[0,1]
	v_pk_add_f32 v[102:103], v[16:17], v[26:27]
	v_pk_add_f32 v[16:17], v[16:17], v[26:27] neg_lo:[0,1] neg_hi:[0,1]
	s_nop 0
	v_pk_mul_f32 v[26:27], v[16:17], s[10:11]
	s_nop 0
	v_pk_fma_f32 v[16:17], v[16:17], s[14:15], v[26:27] op_sel:[0,0,1] op_sel_hi:[1,0,0]
	v_pk_add_f32 v[26:27], v[18:19], v[28:29]
	v_pk_add_f32 v[18:19], v[18:19], v[28:29] neg_lo:[0,1] neg_hi:[0,1]
	v_pk_add_f32 v[28:29], v[20:21], v[30:31]
	v_pk_add_f32 v[20:21], v[20:21], v[30:31] neg_lo:[0,1] neg_hi:[0,1]
	s_nop 0
	v_pk_mul_f32 v[30:31], v[20:21], s[10:11]
	s_nop 0
	v_pk_fma_f32 v[20:21], v[20:21], s[14:15], v[30:31] op_sel:[0,0,1] op_sel_hi:[1,0,0] neg_lo:[1,0,0] neg_hi:[1,0,0]
	v_pk_add_f32 v[30:31], v[0:1], v[8:9] op_sel:[0,1] op_sel_hi:[1,0] neg_hi:[0,1]
	v_pk_add_f32 v[0:1], v[0:1], v[8:9] op_sel:[0,1] op_sel_hi:[1,0] neg_lo:[0,1]
	v_pk_add_f32 v[8:9], v[2:3], v[10:11]
	v_pk_add_f32 v[2:3], v[2:3], v[10:11] neg_lo:[0,1] neg_hi:[0,1]
	s_nop 0
	v_pk_mul_f32 v[10:11], v[2:3], s[10:11]
	s_nop 0
	v_pk_fma_f32 v[2:3], v[2:3], s[14:15], v[10:11] op_sel:[0,0,1] op_sel_hi:[1,0,0]
	v_pk_add_f32 v[10:11], v[4:5], v[12:13]
	v_pk_add_f32 v[4:5], v[4:5], v[12:13] neg_lo:[0,1] neg_hi:[0,1]
	v_pk_add_f32 v[12:13], v[6:7], v[14:15]
	v_pk_add_f32 v[6:7], v[6:7], v[14:15] neg_lo:[0,1] neg_hi:[0,1]
	s_nop 0
	v_pk_mul_f32 v[14:15], v[6:7], s[10:11]
	s_nop 0
	v_pk_fma_f32 v[6:7], v[6:7], s[14:15], v[14:15] op_sel:[0,0,1] op_sel_hi:[1,0,0] neg_lo:[1,0,0] neg_hi:[1,0,0]
	v_pk_add_f32 v[14:15], v[24:25], v[26:27]
	v_pk_add_f32 v[24:25], v[24:25], v[26:27] neg_lo:[0,1] neg_hi:[0,1]
	v_pk_add_f32 v[26:27], v[102:103], v[28:29]
	v_pk_add_f32 v[28:29], v[102:103], v[28:29] neg_lo:[0,1] neg_hi:[0,1]
	v_pk_add_f32 v[102:103], v[22:23], v[18:19] op_sel:[0,1] op_sel_hi:[1,0] neg_hi:[0,1]
	v_pk_add_f32 v[18:19], v[22:23], v[18:19] op_sel:[0,1] op_sel_hi:[1,0] neg_lo:[0,1]
	v_pk_add_f32 v[22:23], v[16:17], v[20:21]
	v_pk_add_f32 v[16:17], v[16:17], v[20:21] neg_lo:[0,1] neg_hi:[0,1]
	v_pk_add_f32 v[20:21], v[30:31], v[10:11]
	v_pk_add_f32 v[10:11], v[30:31], v[10:11] neg_lo:[0,1] neg_hi:[0,1]
	v_pk_add_f32 v[30:31], v[8:9], v[12:13]
	v_pk_add_f32 v[8:9], v[8:9], v[12:13] neg_lo:[0,1] neg_hi:[0,1]
	v_pk_add_f32 v[12:13], v[0:1], v[4:5] op_sel:[0,1] op_sel_hi:[1,0] neg_hi:[0,1]
	v_pk_add_f32 v[0:1], v[0:1], v[4:5] op_sel:[0,1] op_sel_hi:[1,0] neg_lo:[0,1]
	v_pk_add_f32 v[4:5], v[2:3], v[6:7]
	v_pk_add_f32 v[2:3], v[2:3], v[6:7] neg_lo:[0,1] neg_hi:[0,1]
	s_nop 0
	v_pk_mul_f32 v[2:3], v[2:3], s[22:23]
	v_pk_add_f32 v[6:7], v[14:15], v[26:27]
	v_pk_add_f32 v[14:15], v[14:15], v[26:27] neg_lo:[0,1] neg_hi:[0,1]
	v_pk_add_f32 v[26:27], v[24:25], v[28:29] op_sel:[0,1] op_sel_hi:[1,0] neg_hi:[0,1]
	v_pk_add_f32 v[24:25], v[24:25], v[28:29] op_sel:[0,1] op_sel_hi:[1,0] neg_lo:[0,1]
	v_pk_add_f32 v[28:29], v[102:103], v[22:23]
	v_pk_add_f32 v[22:23], v[102:103], v[22:23] neg_lo:[0,1] neg_hi:[0,1]
	v_pk_add_f32 v[102:103], v[18:19], v[16:17] op_sel:[0,1] op_sel_hi:[1,0] neg_hi:[0,1]
	v_pk_add_f32 v[16:17], v[18:19], v[16:17] op_sel:[0,1] op_sel_hi:[1,0] neg_lo:[0,1]
	v_pk_add_f32 v[18:19], v[20:21], v[30:31]
	v_pk_add_f32 v[20:21], v[20:21], v[30:31] neg_lo:[0,1] neg_hi:[0,1]
	v_pk_add_f32 v[30:31], v[10:11], v[8:9] op_sel:[0,1] op_sel_hi:[1,0] neg_hi:[0,1]
	v_pk_add_f32 v[8:9], v[10:11], v[8:9] op_sel:[0,1] op_sel_hi:[1,0] neg_lo:[0,1]
	v_pk_add_f32 v[10:11], v[12:13], v[4:5]
	v_pk_add_f32 v[4:5], v[12:13], v[4:5] neg_lo:[0,1] neg_hi:[0,1]
	v_pk_add_f32 v[12:13], v[0:1], v[2:3] op_sel:[0,1] op_sel_hi:[1,0]
	v_pk_add_f32 v[0:1], v[0:1], v[2:3] op_sel:[0,1] op_sel_hi:[1,0] neg_lo:[0,1] neg_hi:[0,1]
	v_lshlrev_b32_e32 v2, 4, v47
	v_and_or_b32 v2, v2, s15, v81
	v_ashrrev_i32_e32 v3, 4, v2
	v_lshlrev_b32_e32 v3, 3, v3
	v_lshlrev_b32_e32 v2, 3, v2
	v_add3_u32 v2, 0, v3, v2
	ds_write_b64 v2, v[6:7]
	ds_write_b64 v2, v[14:15] offset:34816
	ds_write_b64 v2, v[26:27] offset:17408
	ds_write_b64 v2, v[24:25] offset:52224
	ds_write_b64 v2, v[28:29] offset:8704
	ds_write_b64 v2, v[22:23] offset:43520
	ds_write_b64 v2, v[102:103] offset:26112
	ds_write_b64 v2, v[16:17] offset:60928
	ds_write_b64 v2, v[18:19] offset:4352
	ds_write_b64 v2, v[20:21] offset:39168
	ds_write_b64 v2, v[30:31] offset:21760
	ds_write_b64 v2, v[8:9] offset:56576
	ds_write_b64 v2, v[10:11] offset:13056
	ds_write_b64 v2, v[4:5] offset:47872
	ds_write_b64 v2, v[12:13] offset:30464
	ds_write_b64 v2, v[0:1] offset:65280
	s_waitcnt lgkmcnt(0)
	s_barrier
	s_and_saveexec_b64 s[0:1], s[42:43]
	s_cbranch_execz .LBB0_448
	v_lshl_add_u64 v[2:3], v[78:79], 0, v[172:173]
	s_mov_b64 s[4:5], 0x40000
	v_lshl_add_u64 v[0:1], v[2:3], 0, s[4:5]
	v_add_co_u32_e32 v2, vcc, 0x40000, v2
	v_cmp_ne_u32_e64 s[44:45], 0, v39
	s_nop 0
	v_addc_co_u32_e32 v3, vcc, 0, v3, vcc
	global_load_dwordx4 v[12:15], v[2:3], off
	global_load_dwordx4 v[8:11], v[0:1], off offset:16
	v_mov_b32_e32 v19, 0
	v_mov_b32_e32 v18, 0
	v_mov_b32_e32 v33, 0
	s_and_saveexec_b64 s[4:5], s[44:45]
	s_cbranch_execz .LBB0_441
	global_load_ushort v33, v[0:1], off offset:-2

.LBB0_490:
	s_or_b64 exec, exec, s[0:1]
	v_mov_b32_e32 v37, v32
	s_waitcnt lgkmcnt(0)
	s_barrier
	v_lshl_add_u64 v[224:225], v[78:79], 0, v[172:173]
	s_mov_b64 s[100:101], 0x80000
	v_lshl_add_u64 v[228:229], v[224:225], 0, s[100:101]
	global_load_dword v226, v[228:229], off
	s_mov_b64 s[100:101], 0x140000
	v_lshl_add_u64 v[228:229], v[224:225], 0, s[100:101]
	global_load_dword v226, v[228:229], off
	s_mov_b32 s11, s14
	v_and_b32_e32 v47, 31, v37
	v_cvt_f32_ubyte0_e32 v24, v47
	v_mul_f32_e32 v81, 0x3b000000, v24
	v_sin_f32_e32 v24, v81
	v_ashrrev_i32_e32 v0, 4, v37
	v_lshlrev_b32_e32 v0, 3, v0
	v_lshlrev_b32_e32 v1, 3, v37
	v_cos_f32_e32 v84, v81
	v_add3_u32 v25, 0, v0, v1
	ds_read_b64 v[0:1], v25
	ds_read_b64 v[2:3], v25 offset:4352
	ds_read_b64 v[4:5], v25 offset:8704
	ds_read_b64 v[6:7], v25 offset:13056
	ds_read_b64 v[8:9], v25 offset:17408
	ds_read_b64 v[10:11], v25 offset:21760
	ds_read_b64 v[12:13], v25 offset:26112
	ds_read_b64 v[14:15], v25 offset:30464
	ds_read_b64 v[16:17], v25 offset:34816
	ds_read_b64 v[18:19], v25 offset:39168
	ds_read_b64 v[20:21], v25 offset:43520
	ds_read_b64 v[22:23], v25 offset:47872
	v_xor_b32_e32 v85, 0x80000000, v24
	s_waitcnt lgkmcnt(10)
	v_pk_mul_f32 v[118:119], v[2:3], v[24:25] op_sel:[1,0] op_sel_hi:[0,0] neg_hi:[0,1]
	v_pk_fma_f32 v[2:3], v[2:3], v[84:85], v[118:119] op_sel_hi:[1,0,1]
	v_pk_mul_f32 v[118:119], v[24:25], v[84:85] op_sel:[0,1] op_sel_hi:[0,0] neg_hi:[1,0]
	v_pk_fma_f32 v[118:119], v[84:85], v[84:85], v[118:119] op_sel_hi:[0,1,1]
	ds_read_b64 v[26:27], v25 offset:52224
	ds_read_b64 v[28:29], v25 offset:56576
	ds_read_b64 v[30:31], v25 offset:60928
	ds_read_b64 v[82:83], v25 offset:65280
	s_waitcnt lgkmcnt(13)
	v_pk_mul_f32 v[120:121], v[4:5], v[118:119] op_sel:[1,1] op_sel_hi:[0,1] neg_lo:[0,1]
	v_pk_fma_f32 v[4:5], v[4:5], v[118:119], v[120:121] op_sel_hi:[1,0,1]
	v_pk_mul_f32 v[120:121], v[24:25], v[118:119] op_sel:[0,1] op_sel_hi:[0,0] neg_hi:[1,0]
	v_pk_fma_f32 v[118:119], v[84:85], v[118:119], v[120:121] op_sel_hi:[0,1,1]
	s_mov_b32 s35, s30
	s_waitcnt lgkmcnt(12)
	v_pk_mul_f32 v[120:121], v[6:7], v[118:119] op_sel:[1,1] op_sel_hi:[0,1] neg_lo:[0,1]
	v_pk_fma_f32 v[6:7], v[6:7], v[118:119], v[120:121] op_sel_hi:[1,0,1]
	v_pk_mul_f32 v[120:121], v[24:25], v[118:119] op_sel:[0,1] op_sel_hi:[0,0] neg_hi:[1,0]
	v_pk_fma_f32 v[118:119], v[84:85], v[118:119], v[120:121] op_sel_hi:[0,1,1]
	s_mov_b32 s0, s19
	s_waitcnt lgkmcnt(11)
	v_pk_mul_f32 v[120:121], v[8:9], v[118:119] op_sel:[1,1] op_sel_hi:[0,1] neg_lo:[0,1]
	v_pk_fma_f32 v[8:9], v[8:9], v[118:119], v[120:121] op_sel_hi:[1,0,1]
	v_pk_mul_f32 v[120:121], v[24:25], v[118:119] op_sel:[0,1] op_sel_hi:[0,0] neg_hi:[1,0]
	v_pk_fma_f32 v[118:119], v[84:85], v[118:119], v[120:121] op_sel_hi:[0,1,1]
	s_waitcnt lgkmcnt(0)
	v_pk_mul_f32 v[120:121], v[10:11], v[118:119] op_sel:[1,1] op_sel_hi:[0,1] neg_lo:[0,1]
	v_pk_fma_f32 v[10:11], v[10:11], v[118:119], v[120:121] op_sel_hi:[1,0,1]
	v_pk_mul_f32 v[120:121], v[24:25], v[118:119] op_sel:[0,1] op_sel_hi:[0,0] neg_hi:[1,0]
	v_pk_fma_f32 v[118:119], v[84:85], v[118:119], v[120:121] op_sel_hi:[0,1,1]
	s_barrier
	v_pk_mul_f32 v[120:121], v[12:13], v[118:119] op_sel:[1,1] op_sel_hi:[0,1] neg_lo:[0,1]
	v_pk_fma_f32 v[12:13], v[12:13], v[118:119], v[120:121] op_sel_hi:[1,0,1]
	v_pk_mul_f32 v[120:121], v[24:25], v[118:119] op_sel:[0,1] op_sel_hi:[0,0] neg_hi:[1,0]
	v_pk_fma_f32 v[118:119], v[84:85], v[118:119], v[120:121] op_sel_hi:[0,1,1]
	s_nop 0
	v_pk_mul_f32 v[120:121], v[14:15], v[118:119] op_sel:[1,1] op_sel_hi:[0,1] neg_lo:[0,1]
	v_pk_fma_f32 v[14:15], v[14:15], v[118:119], v[120:121] op_sel_hi:[1,0,1]
	v_pk_mul_f32 v[120:121], v[24:25], v[118:119] op_sel:[0,1] op_sel_hi:[0,0] neg_hi:[1,0]
	v_pk_fma_f32 v[118:119], v[84:85], v[118:119], v[120:121] op_sel_hi:[0,1,1]
	s_nop 0
	v_pk_mul_f32 v[120:121], v[16:17], v[118:119] op_sel:[1,1] op_sel_hi:[0,1] neg_lo:[0,1]
	v_pk_fma_f32 v[16:17], v[16:17], v[118:119], v[120:121] op_sel_hi:[1,0,1]
	v_pk_mul_f32 v[120:121], v[24:25], v[118:119] op_sel:[0,1] op_sel_hi:[0,0] neg_hi:[1,0]
	v_pk_fma_f32 v[118:119], v[84:85], v[118:119], v[120:121] op_sel_hi:[0,1,1]
	s_nop 0
	v_pk_mul_f32 v[120:121], v[18:19], v[118:119] op_sel:[1,1] op_sel_hi:[0,1] neg_lo:[0,1]
	v_pk_fma_f32 v[18:19], v[18:19], v[118:119], v[120:121] op_sel_hi:[1,0,1]
	v_pk_mul_f32 v[120:121], v[24:25], v[118:119] op_sel:[0,1] op_sel_hi:[0,0] neg_hi:[1,0]
	v_pk_fma_f32 v[118:119], v[84:85], v[118:119], v[120:121] op_sel_hi:[0,1,1]
	s_nop 0
	v_pk_mul_f32 v[120:121], v[20:21], v[118:119] op_sel:[1,1] op_sel_hi:[0,1] neg_lo:[0,1]
	v_pk_fma_f32 v[20:21], v[20:21], v[118:119], v[120:121] op_sel_hi:[1,0,1]
	v_pk_mul_f32 v[120:121], v[24:25], v[118:119] op_sel:[0,1] op_sel_hi:[0,0] neg_hi:[1,0]
	v_pk_fma_f32 v[118:119], v[84:85], v[118:119], v[120:121] op_sel_hi:[0,1,1]
	s_nop 0
	v_pk_mul_f32 v[120:121], v[22:23], v[118:119] op_sel:[1,1] op_sel_hi:[0,1] neg_lo:[0,1]
	v_pk_fma_f32 v[22:23], v[22:23], v[118:119], v[120:121] op_sel_hi:[1,0,1]
	v_pk_mul_f32 v[120:121], v[24:25], v[118:119] op_sel:[0,1] op_sel_hi:[0,0] neg_hi:[1,0]
	v_pk_fma_f32 v[118:119], v[84:85], v[118:119], v[120:121] op_sel_hi:[0,1,1]
	s_nop 0
	v_pk_mul_f32 v[120:121], v[26:27], v[118:119] op_sel:[1,1] op_sel_hi:[0,1] neg_lo:[0,1]
	v_pk_fma_f32 v[26:27], v[26:27], v[118:119], v[120:121] op_sel_hi:[1,0,1]
	v_pk_mul_f32 v[120:121], v[24:25], v[118:119] op_sel:[0,1] op_sel_hi:[0,0] neg_hi:[1,0]
	v_pk_fma_f32 v[118:119], v[84:85], v[118:119], v[120:121] op_sel_hi:[0,1,1]
	s_nop 0
	v_pk_mul_f32 v[120:121], v[28:29], v[118:119] op_sel:[1,1] op_sel_hi:[0,1] neg_lo:[0,1]
	v_pk_fma_f32 v[28:29], v[28:29], v[118:119], v[120:121] op_sel_hi:[1,0,1]
	v_pk_mul_f32 v[120:121], v[24:25], v[118:119] op_sel:[0,1] op_sel_hi:[0,0] neg_hi:[1,0]
	v_pk_fma_f32 v[118:119], v[84:85], v[118:119], v[120:121] op_sel_hi:[0,1,1]
	v_pk_mul_f32 v[24:25], v[24:25], v[118:119] op_sel:[0,1] op_sel_hi:[0,0] neg_hi:[1,0]
	v_pk_fma_f32 v[24:25], v[84:85], v[118:119], v[24:25] op_sel_hi:[0,1,1]
	v_pk_mul_f32 v[84:85], v[82:83], v[24:25] op_sel:[1,1] op_sel_hi:[0,1] neg_lo:[0,1]
	v_pk_fma_f32 v[24:25], v[82:83], v[24:25], v[84:85] op_sel_hi:[1,0,1]
	v_pk_add_f32 v[82:83], v[0:1], v[16:17]
	v_pk_add_f32 v[0:1], v[0:1], v[16:17] neg_lo:[0,1] neg_hi:[0,1]
	v_pk_add_f32 v[16:17], v[2:3], v[18:19]
	v_pk_add_f32 v[2:3], v[2:3], v[18:19] neg_lo:[0,1] neg_hi:[0,1]
	v_pk_mul_f32 v[120:121], v[30:31], v[118:119] op_sel:[1,1] op_sel_hi:[0,1] neg_lo:[0,1]
	v_pk_mul_f32 v[18:19], v[2:3], s[18:19]
	v_pk_fma_f32 v[30:31], v[30:31], v[118:119], v[120:121] op_sel_hi:[1,0,1]
	v_pk_fma_f32 v[2:3], v[2:3], s[30:31], v[18:19] op_sel:[0,0,1] op_sel_hi:[1,0,0]
	v_pk_add_f32 v[18:19], v[4:5], v[20:21]
	v_pk_add_f32 v[4:5], v[4:5], v[20:21] neg_lo:[0,1] neg_hi:[0,1]
	s_nop 0
	v_pk_mul_f32 v[20:21], v[4:5], s[10:11]
	s_nop 0
	v_pk_fma_f32 v[4:5], v[4:5], s[14:15], v[20:21] op_sel:[0,0,1] op_sel_hi:[1,0,0]
	v_pk_add_f32 v[20:21], v[6:7], v[22:23]
	v_pk_add_f32 v[6:7], v[6:7], v[22:23] neg_lo:[0,1] neg_hi:[0,1]
	s_nop 0
	v_pk_mul_f32 v[22:23], v[6:7], s[34:35]
	s_nop 0
	v_pk_fma_f32 v[6:7], v[6:7], s[0:1], v[22:23] op_sel:[0,0,1] op_sel_hi:[1,0,0]
	v_pk_add_f32 v[22:23], v[8:9], v[26:27]
	v_pk_add_f32 v[8:9], v[8:9], v[26:27] neg_lo:[0,1] neg_hi:[0,1]
	v_pk_add_f32 v[26:27], v[10:11], v[28:29]
	v_pk_add_f32 v[10:11], v[10:11], v[28:29] neg_lo:[0,1] neg_hi:[0,1]
	s_nop 0
	v_pk_mul_f32 v[28:29], v[10:11], s[34:35]
	s_nop 0
	v_pk_fma_f32 v[10:11], v[10:11], s[0:1], v[28:29] op_sel:[0,0,1] op_sel_hi:[1,0,0] neg_lo:[1,0,0] neg_hi:[1,0,0]
	v_pk_add_f32 v[28:29], v[12:13], v[30:31]
	v_pk_add_f32 v[12:13], v[12:13], v[30:31] neg_lo:[0,1] neg_hi:[0,1]
	s_nop 0
	v_pk_mul_f32 v[30:31], v[12:13], s[10:11]
	s_nop 0
	v_pk_fma_f32 v[12:13], v[12:13], s[14:15], v[30:31] op_sel:[0,0,1] op_sel_hi:[1,0,0] neg_lo:[1,0,0] neg_hi:[1,0,0]
	v_pk_add_f32 v[30:31], v[14:15], v[24:25]
	v_pk_add_f32 v[14:15], v[14:15], v[24:25] neg_lo:[0,1] neg_hi:[0,1]
	s_nop 0
	v_pk_mul_f32 v[24:25], v[14:15], s[18:19]
	s_nop 0
	v_pk_fma_f32 v[14:15], v[14:15], s[30:31], v[24:25] op_sel:[0,0,1] op_sel_hi:[1,0,0] neg_lo:[1,0,0] neg_hi:[1,0,0]
	v_pk_add_f32 v[24:25], v[82:83], v[22:23]
	v_pk_add_f32 v[22:23], v[82:83], v[22:23] neg_lo:[0,1] neg_hi:[0,1]
	v_pk_add_f32 v[82:83], v[16:17], v[26:27]
	v_pk_add_f32 v[16:17], v[16:17], v[26:27] neg_lo:[0,1] neg_hi:[0,1]
	s_nop 0
	v_pk_mul_f32 v[26:27], v[16:17], s[10:11]
	s_nop 0
	v_pk_fma_f32 v[16:17], v[16:17], s[14:15], v[26:27] op_sel:[0,0,1] op_sel_hi:[1,0,0]
	v_pk_add_f32 v[26:27], v[18:19], v[28:29]
	v_pk_add_f32 v[18:19], v[18:19], v[28:29] neg_lo:[0,1] neg_hi:[0,1]
	v_pk_add_f32 v[28:29], v[20:21], v[30:31]
	v_pk_add_f32 v[20:21], v[20:21], v[30:31] neg_lo:[0,1] neg_hi:[0,1]
	s_nop 0
	v_pk_mul_f32 v[30:31], v[20:21], s[10:11]
	s_nop 0
	v_pk_fma_f32 v[20:21], v[20:21], s[14:15], v[30:31] op_sel:[0,0,1] op_sel_hi:[1,0,0] neg_lo:[1,0,0] neg_hi:[1,0,0]
	v_pk_add_f32 v[30:31], v[0:1], v[8:9] op_sel:[0,1] op_sel_hi:[1,0] neg_hi:[0,1]
	v_pk_add_f32 v[0:1], v[0:1], v[8:9] op_sel:[0,1] op_sel_hi:[1,0] neg_lo:[0,1]
	v_pk_add_f32 v[8:9], v[2:3], v[10:11]
	v_pk_add_f32 v[2:3], v[2:3], v[10:11] neg_lo:[0,1] neg_hi:[0,1]
	s_nop 0
	v_pk_mul_f32 v[10:11], v[2:3], s[10:11]
	s_nop 0
	v_pk_fma_f32 v[2:3], v[2:3], s[14:15], v[10:11] op_sel:[0,0,1] op_sel_hi:[1,0,0]
	v_pk_add_f32 v[10:11], v[4:5], v[12:13]
	v_pk_add_f32 v[4:5], v[4:5], v[12:13] neg_lo:[0,1] neg_hi:[0,1]
	v_pk_add_f32 v[12:13], v[6:7], v[14:15]
	v_pk_add_f32 v[6:7], v[6:7], v[14:15] neg_lo:[0,1] neg_hi:[0,1]
	s_nop 0
	v_pk_mul_f32 v[14:15], v[6:7], s[10:11]
	s_nop 0
	v_pk_fma_f32 v[6:7], v[6:7], s[14:15], v[14:15] op_sel:[0,0,1] op_sel_hi:[1,0,0] neg_lo:[1,0,0] neg_hi:[1,0,0]
	v_pk_add_f32 v[14:15], v[24:25], v[26:27]
	v_pk_add_f32 v[24:25], v[24:25], v[26:27] neg_lo:[0,1] neg_hi:[0,1]
	v_pk_add_f32 v[26:27], v[82:83], v[28:29]
	v_pk_add_f32 v[28:29], v[82:83], v[28:29] neg_lo:[0,1] neg_hi:[0,1]
	v_pk_add_f32 v[82:83], v[22:23], v[18:19] op_sel:[0,1] op_sel_hi:[1,0] neg_hi:[0,1]
	v_pk_add_f32 v[18:19], v[22:23], v[18:19] op_sel:[0,1] op_sel_hi:[1,0] neg_lo:[0,1]
	v_pk_add_f32 v[22:23], v[16:17], v[20:21]
	v_pk_add_f32 v[16:17], v[16:17], v[20:21] neg_lo:[0,1] neg_hi:[0,1]
	v_pk_add_f32 v[20:21], v[30:31], v[10:11]
	v_pk_add_f32 v[10:11], v[30:31], v[10:11] neg_lo:[0,1] neg_hi:[0,1]
	v_pk_add_f32 v[30:31], v[8:9], v[12:13]
	v_pk_add_f32 v[8:9], v[8:9], v[12:13] neg_lo:[0,1] neg_hi:[0,1]
	v_pk_add_f32 v[12:13], v[0:1], v[4:5] op_sel:[0,1] op_sel_hi:[1,0] neg_hi:[0,1]
	v_pk_add_f32 v[0:1], v[0:1], v[4:5] op_sel:[0,1] op_sel_hi:[1,0] neg_lo:[0,1]
	v_pk_add_f32 v[4:5], v[2:3], v[6:7]
	v_pk_add_f32 v[2:3], v[2:3], v[6:7] neg_lo:[0,1] neg_hi:[0,1]
	s_nop 0
	v_pk_mul_f32 v[2:3], v[2:3], s[22:23]
	v_pk_add_f32 v[6:7], v[14:15], v[26:27]
	v_pk_add_f32 v[14:15], v[14:15], v[26:27] neg_lo:[0,1] neg_hi:[0,1]
	v_pk_add_f32 v[26:27], v[24:25], v[28:29] op_sel:[0,1] op_sel_hi:[1,0] neg_hi:[0,1]
	v_pk_add_f32 v[24:25], v[24:25], v[28:29] op_sel:[0,1] op_sel_hi:[1,0] neg_lo:[0,1]
	v_pk_add_f32 v[28:29], v[82:83], v[22:23]
	v_pk_add_f32 v[22:23], v[82:83], v[22:23] neg_lo:[0,1] neg_hi:[0,1]
	v_pk_add_f32 v[82:83], v[18:19], v[16:17] op_sel:[0,1] op_sel_hi:[1,0] neg_hi:[0,1]
	v_pk_add_f32 v[16:17], v[18:19], v[16:17] op_sel:[0,1] op_sel_hi:[1,0] neg_lo:[0,1]
	v_pk_add_f32 v[18:19], v[20:21], v[30:31]
	v_pk_add_f32 v[20:21], v[20:21], v[30:31] neg_lo:[0,1] neg_hi:[0,1]
	v_pk_add_f32 v[30:31], v[10:11], v[8:9] op_sel:[0,1] op_sel_hi:[1,0] neg_hi:[0,1]
	v_pk_add_f32 v[8:9], v[10:11], v[8:9] op_sel:[0,1] op_sel_hi:[1,0] neg_lo:[0,1]
	v_pk_add_f32 v[10:11], v[12:13], v[4:5]
	v_pk_add_f32 v[4:5], v[12:13], v[4:5] neg_lo:[0,1] neg_hi:[0,1]
	v_pk_add_f32 v[12:13], v[0:1], v[2:3] op_sel:[0,1] op_sel_hi:[1,0]
	v_pk_add_f32 v[0:1], v[0:1], v[2:3] op_sel:[0,1] op_sel_hi:[1,0] neg_lo:[0,1] neg_hi:[0,1]
	v_lshlrev_b32_e32 v2, 4, v37
	v_and_or_b32 v2, v2, s7, v47
	v_ashrrev_i32_e32 v3, 4, v2
	v_lshlrev_b32_e32 v3, 3, v3
	v_lshlrev_b32_e32 v2, 3, v2
	v_add3_u32 v2, 0, v3, v2
	v_add_u32_e32 v3, 0x800, v2
	v_mov_b32_e32 v37, v32
	ds_write2_b64 v2, v[6:7], v[18:19] offset1:34
	ds_write2_b64 v3, v[14:15], v[20:21] offset0:16 offset1:50
	ds_write2_b64 v2, v[26:27], v[30:31] offset0:136 offset1:170
	ds_write2_b64 v3, v[24:25], v[8:9] offset0:152 offset1:186
	ds_write2_b64 v2, v[28:29], v[10:11] offset0:68 offset1:102
	ds_write2_b64 v3, v[22:23], v[4:5] offset0:84 offset1:118
	ds_write2_b64 v2, v[82:83], v[12:13] offset0:204 offset1:238
	ds_write2_b64 v3, v[16:17], v[0:1] offset0:220 offset1:254
	s_waitcnt lgkmcnt(0)
	s_barrier
	s_nop 0
	v_and_b32_e32 v47, 0x1ff, v37
	v_cvt_f32_u32_e32 v24, v47
	v_ashrrev_i32_e32 v0, 4, v37
	v_lshlrev_b32_e32 v0, 3, v0
	v_lshlrev_b32_e32 v1, 3, v37
	v_mul_f32_e32 v81, 0x39000000, v24
	v_sin_f32_e32 v24, v81
	v_cos_f32_e32 v84, v81
	v_add3_u32 v25, 0, v0, v1
	ds_read_b64 v[0:1], v25
	ds_read_b64 v[2:3], v25 offset:4352
	ds_read_b64 v[4:5], v25 offset:8704
	ds_read_b64 v[6:7], v25 offset:13056
	ds_read_b64 v[8:9], v25 offset:17408
	ds_read_b64 v[10:11], v25 offset:21760
	ds_read_b64 v[12:13], v25 offset:26112
	ds_read_b64 v[14:15], v25 offset:30464
	v_xor_b32_e32 v85, 0x80000000, v24
	s_waitcnt lgkmcnt(6)
	v_pk_mul_f32 v[118:119], v[2:3], v[24:25] op_sel:[1,0] op_sel_hi:[0,0] neg_hi:[0,1]
	v_pk_fma_f32 v[2:3], v[2:3], v[84:85], v[118:119] op_sel_hi:[1,0,1]
	v_pk_mul_f32 v[118:119], v[24:25], v[84:85] op_sel:[0,1] op_sel_hi:[0,0] neg_hi:[1,0]
	v_pk_fma_f32 v[118:119], v[84:85], v[84:85], v[118:119] op_sel_hi:[0,1,1]
	ds_read_b64 v[16:17], v25 offset:34816
	ds_read_b64 v[18:19], v25 offset:39168
	ds_read_b64 v[20:21], v25 offset:43520
	ds_read_b64 v[22:23], v25 offset:47872
	s_waitcnt lgkmcnt(9)
	v_pk_mul_f32 v[120:121], v[4:5], v[118:119] op_sel:[1,1] op_sel_hi:[0,1] neg_lo:[0,1]
	v_pk_fma_f32 v[4:5], v[4:5], v[118:119], v[120:121] op_sel_hi:[1,0,1]
	v_pk_mul_f32 v[120:121], v[24:25], v[118:119] op_sel:[0,1] op_sel_hi:[0,0] neg_hi:[1,0]
	v_pk_fma_f32 v[118:119], v[84:85], v[118:119], v[120:121] op_sel_hi:[0,1,1]
	ds_read_b64 v[26:27], v25 offset:52224
	ds_read_b64 v[28:29], v25 offset:56576
	ds_read_b64 v[30:31], v25 offset:60928
	ds_read_b64 v[82:83], v25 offset:65280
	s_waitcnt lgkmcnt(12)
	v_pk_mul_f32 v[120:121], v[6:7], v[118:119] op_sel:[1,1] op_sel_hi:[0,1] neg_lo:[0,1]
	v_pk_fma_f32 v[6:7], v[6:7], v[118:119], v[120:121] op_sel_hi:[1,0,1]
	v_pk_mul_f32 v[120:121], v[24:25], v[118:119] op_sel:[0,1] op_sel_hi:[0,0] neg_hi:[1,0]
	v_pk_fma_f32 v[118:119], v[84:85], v[118:119], v[120:121] op_sel_hi:[0,1,1]
	s_waitcnt lgkmcnt(0)
	v_pk_mul_f32 v[120:121], v[8:9], v[118:119] op_sel:[1,1] op_sel_hi:[0,1] neg_lo:[0,1]
	v_pk_fma_f32 v[8:9], v[8:9], v[118:119], v[120:121] op_sel_hi:[1,0,1]
	v_pk_mul_f32 v[120:121], v[24:25], v[118:119] op_sel:[0,1] op_sel_hi:[0,0] neg_hi:[1,0]
	v_pk_fma_f32 v[118:119], v[84:85], v[118:119], v[120:121] op_sel_hi:[0,1,1]
	s_barrier
	v_pk_mul_f32 v[120:121], v[10:11], v[118:119] op_sel:[1,1] op_sel_hi:[0,1] neg_lo:[0,1]
	v_pk_fma_f32 v[10:11], v[10:11], v[118:119], v[120:121] op_sel_hi:[1,0,1]
	v_pk_mul_f32 v[120:121], v[24:25], v[118:119] op_sel:[0,1] op_sel_hi:[0,0] neg_hi:[1,0]
	v_pk_fma_f32 v[118:119], v[84:85], v[118:119], v[120:121] op_sel_hi:[0,1,1]
	s_nop 0
	v_pk_mul_f32 v[120:121], v[12:13], v[118:119] op_sel:[1,1] op_sel_hi:[0,1] neg_lo:[0,1]
	v_pk_fma_f32 v[12:13], v[12:13], v[118:119], v[120:121] op_sel_hi:[1,0,1]
	v_pk_mul_f32 v[120:121], v[24:25], v[118:119] op_sel:[0,1] op_sel_hi:[0,0] neg_hi:[1,0]
	v_pk_fma_f32 v[118:119], v[84:85], v[118:119], v[120:121] op_sel_hi:[0,1,1]
	s_nop 0
	v_pk_mul_f32 v[120:121], v[14:15], v[118:119] op_sel:[1,1] op_sel_hi:[0,1] neg_lo:[0,1]
	v_pk_fma_f32 v[14:15], v[14:15], v[118:119], v[120:121] op_sel_hi:[1,0,1]
	v_pk_mul_f32 v[120:121], v[24:25], v[118:119] op_sel:[0,1] op_sel_hi:[0,0] neg_hi:[1,0]
	v_pk_fma_f32 v[118:119], v[84:85], v[118:119], v[120:121] op_sel_hi:[0,1,1]
	s_nop 0
	v_pk_mul_f32 v[120:121], v[16:17], v[118:119] op_sel:[1,1] op_sel_hi:[0,1] neg_lo:[0,1]
	v_pk_fma_f32 v[16:17], v[16:17], v[118:119], v[120:121] op_sel_hi:[1,0,1]
	v_pk_mul_f32 v[120:121], v[24:25], v[118:119] op_sel:[0,1] op_sel_hi:[0,0] neg_hi:[1,0]
	v_pk_fma_f32 v[118:119], v[84:85], v[118:119], v[120:121] op_sel_hi:[0,1,1]
	s_nop 0
	v_pk_mul_f32 v[120:121], v[18:19], v[118:119] op_sel:[1,1] op_sel_hi:[0,1] neg_lo:[0,1]
	v_pk_fma_f32 v[18:19], v[18:19], v[118:119], v[120:121] op_sel_hi:[1,0,1]
	v_pk_mul_f32 v[120:121], v[24:25], v[118:119] op_sel:[0,1] op_sel_hi:[0,0] neg_hi:[1,0]
	v_pk_fma_f32 v[118:119], v[84:85], v[118:119], v[120:121] op_sel_hi:[0,1,1]
	s_nop 0
	v_pk_mul_f32 v[120:121], v[20:21], v[118:119] op_sel:[1,1] op_sel_hi:[0,1] neg_lo:[0,1]
	v_pk_fma_f32 v[20:21], v[20:21], v[118:119], v[120:121] op_sel_hi:[1,0,1]
	v_pk_mul_f32 v[120:121], v[24:25], v[118:119] op_sel:[0,1] op_sel_hi:[0,0] neg_hi:[1,0]
	v_pk_fma_f32 v[118:119], v[84:85], v[118:119], v[120:121] op_sel_hi:[0,1,1]
	s_nop 0
	v_pk_mul_f32 v[120:121], v[22:23], v[118:119] op_sel:[1,1] op_sel_hi:[0,1] neg_lo:[0,1]
	v_pk_fma_f32 v[22:23], v[22:23], v[118:119], v[120:121] op_sel_hi:[1,0,1]
	v_pk_mul_f32 v[120:121], v[24:25], v[118:119] op_sel:[0,1] op_sel_hi:[0,0] neg_hi:[1,0]
	v_pk_fma_f32 v[118:119], v[84:85], v[118:119], v[120:121] op_sel_hi:[0,1,1]
	s_nop 0
	v_pk_mul_f32 v[120:121], v[26:27], v[118:119] op_sel:[1,1] op_sel_hi:[0,1] neg_lo:[0,1]
	v_pk_fma_f32 v[26:27], v[26:27], v[118:119], v[120:121] op_sel_hi:[1,0,1]
	v_pk_mul_f32 v[120:121], v[24:25], v[118:119] op_sel:[0,1] op_sel_hi:[0,0] neg_hi:[1,0]
	v_pk_fma_f32 v[118:119], v[84:85], v[118:119], v[120:121] op_sel_hi:[0,1,1]
	s_nop 0
	v_pk_mul_f32 v[120:121], v[28:29], v[118:119] op_sel:[1,1] op_sel_hi:[0,1] neg_lo:[0,1]
	v_pk_fma_f32 v[28:29], v[28:29], v[118:119], v[120:121] op_sel_hi:[1,0,1]
	v_pk_mul_f32 v[120:121], v[24:25], v[118:119] op_sel:[0,1] op_sel_hi:[0,0] neg_hi:[1,0]
	v_pk_fma_f32 v[118:119], v[84:85], v[118:119], v[120:121] op_sel_hi:[0,1,1]
	v_pk_mul_f32 v[24:25], v[24:25], v[118:119] op_sel:[0,1] op_sel_hi:[0,0] neg_hi:[1,0]
	v_pk_fma_f32 v[24:25], v[84:85], v[118:119], v[24:25] op_sel_hi:[0,1,1]
	v_pk_mul_f32 v[84:85], v[82:83], v[24:25] op_sel:[1,1] op_sel_hi:[0,1] neg_lo:[0,1]
	v_pk_fma_f32 v[24:25], v[82:83], v[24:25], v[84:85] op_sel_hi:[1,0,1]
	v_pk_add_f32 v[82:83], v[0:1], v[16:17]
	v_pk_add_f32 v[0:1], v[0:1], v[16:17] neg_lo:[0,1] neg_hi:[0,1]
	v_pk_add_f32 v[16:17], v[2:3], v[18:19]
	v_pk_add_f32 v[2:3], v[2:3], v[18:19] neg_lo:[0,1] neg_hi:[0,1]
	v_pk_mul_f32 v[120:121], v[30:31], v[118:119] op_sel:[1,1] op_sel_hi:[0,1] neg_lo:[0,1]
	v_pk_mul_f32 v[18:19], v[2:3], s[18:19]
	v_pk_fma_f32 v[30:31], v[30:31], v[118:119], v[120:121] op_sel_hi:[1,0,1]
	v_pk_fma_f32 v[2:3], v[2:3], s[30:31], v[18:19] op_sel:[0,0,1] op_sel_hi:[1,0,0]
	v_pk_add_f32 v[18:19], v[4:5], v[20:21]
	v_pk_add_f32 v[4:5], v[4:5], v[20:21] neg_lo:[0,1] neg_hi:[0,1]
	s_nop 0
	v_pk_mul_f32 v[20:21], v[4:5], s[10:11]
	s_nop 0
	v_pk_fma_f32 v[4:5], v[4:5], s[14:15], v[20:21] op_sel:[0,0,1] op_sel_hi:[1,0,0]
	v_pk_add_f32 v[20:21], v[6:7], v[22:23]
	v_pk_add_f32 v[6:7], v[6:7], v[22:23] neg_lo:[0,1] neg_hi:[0,1]
	s_nop 0
	v_pk_mul_f32 v[22:23], v[6:7], s[34:35]
	s_nop 0
	v_pk_fma_f32 v[6:7], v[6:7], s[0:1], v[22:23] op_sel:[0,0,1] op_sel_hi:[1,0,0]
	v_pk_add_f32 v[22:23], v[8:9], v[26:27]
	v_pk_add_f32 v[8:9], v[8:9], v[26:27] neg_lo:[0,1] neg_hi:[0,1]
	v_pk_add_f32 v[26:27], v[10:11], v[28:29]
	v_pk_add_f32 v[10:11], v[10:11], v[28:29] neg_lo:[0,1] neg_hi:[0,1]
	s_nop 0
	v_pk_mul_f32 v[28:29], v[10:11], s[34:35]
	s_nop 0
	v_pk_fma_f32 v[10:11], v[10:11], s[0:1], v[28:29] op_sel:[0,0,1] op_sel_hi:[1,0,0] neg_lo:[1,0,0] neg_hi:[1,0,0]
	v_pk_add_f32 v[28:29], v[12:13], v[30:31]
	v_pk_add_f32 v[12:13], v[12:13], v[30:31] neg_lo:[0,1] neg_hi:[0,1]
	s_nop 0
	v_pk_mul_f32 v[30:31], v[12:13], s[10:11]
	s_nop 0
	v_pk_fma_f32 v[12:13], v[12:13], s[14:15], v[30:31] op_sel:[0,0,1] op_sel_hi:[1,0,0] neg_lo:[1,0,0] neg_hi:[1,0,0]
	v_pk_add_f32 v[30:31], v[14:15], v[24:25]
	v_pk_add_f32 v[14:15], v[14:15], v[24:25] neg_lo:[0,1] neg_hi:[0,1]
	s_nop 0
	v_pk_mul_f32 v[24:25], v[14:15], s[18:19]
	s_nop 0
	v_pk_fma_f32 v[14:15], v[14:15], s[30:31], v[24:25] op_sel:[0,0,1] op_sel_hi:[1,0,0] neg_lo:[1,0,0] neg_hi:[1,0,0]
	v_pk_add_f32 v[24:25], v[82:83], v[22:23]
	v_pk_add_f32 v[22:23], v[82:83], v[22:23] neg_lo:[0,1] neg_hi:[0,1]
	v_pk_add_f32 v[82:83], v[16:17], v[26:27]
	v_pk_add_f32 v[16:17], v[16:17], v[26:27] neg_lo:[0,1] neg_hi:[0,1]
	s_nop 0
	v_pk_mul_f32 v[26:27], v[16:17], s[10:11]
	s_nop 0
	v_pk_fma_f32 v[16:17], v[16:17], s[14:15], v[26:27] op_sel:[0,0,1] op_sel_hi:[1,0,0]
	v_pk_add_f32 v[26:27], v[18:19], v[28:29]
	v_pk_add_f32 v[18:19], v[18:19], v[28:29] neg_lo:[0,1] neg_hi:[0,1]
	v_pk_add_f32 v[28:29], v[20:21], v[30:31]
	v_pk_add_f32 v[20:21], v[20:21], v[30:31] neg_lo:[0,1] neg_hi:[0,1]
	s_nop 0
	v_pk_mul_f32 v[30:31], v[20:21], s[10:11]
	s_nop 0
	v_pk_fma_f32 v[20:21], v[20:21], s[14:15], v[30:31] op_sel:[0,0,1] op_sel_hi:[1,0,0] neg_lo:[1,0,0] neg_hi:[1,0,0]
	v_pk_add_f32 v[30:31], v[0:1], v[8:9] op_sel:[0,1] op_sel_hi:[1,0] neg_hi:[0,1]
	v_pk_add_f32 v[0:1], v[0:1], v[8:9] op_sel:[0,1] op_sel_hi:[1,0] neg_lo:[0,1]
	v_pk_add_f32 v[8:9], v[2:3], v[10:11]
	v_pk_add_f32 v[2:3], v[2:3], v[10:11] neg_lo:[0,1] neg_hi:[0,1]
	s_nop 0
	v_pk_mul_f32 v[10:11], v[2:3], s[10:11]
	s_nop 0
	v_pk_fma_f32 v[2:3], v[2:3], s[14:15], v[10:11] op_sel:[0,0,1] op_sel_hi:[1,0,0]
	v_pk_add_f32 v[10:11], v[4:5], v[12:13]
	v_pk_add_f32 v[4:5], v[4:5], v[12:13] neg_lo:[0,1] neg_hi:[0,1]
	v_pk_add_f32 v[12:13], v[6:7], v[14:15]
	v_pk_add_f32 v[6:7], v[6:7], v[14:15] neg_lo:[0,1] neg_hi:[0,1]
	s_nop 0
	v_pk_mul_f32 v[14:15], v[6:7], s[10:11]
	s_nop 0
	v_pk_fma_f32 v[6:7], v[6:7], s[14:15], v[14:15] op_sel:[0,0,1] op_sel_hi:[1,0,0] neg_lo:[1,0,0] neg_hi:[1,0,0]
	v_pk_add_f32 v[14:15], v[24:25], v[26:27]
	v_pk_add_f32 v[24:25], v[24:25], v[26:27] neg_lo:[0,1] neg_hi:[0,1]
	v_pk_add_f32 v[26:27], v[82:83], v[28:29]
	v_pk_add_f32 v[28:29], v[82:83], v[28:29] neg_lo:[0,1] neg_hi:[0,1]
	v_pk_add_f32 v[82:83], v[22:23], v[18:19] op_sel:[0,1] op_sel_hi:[1,0] neg_hi:[0,1]
	v_pk_add_f32 v[18:19], v[22:23], v[18:19] op_sel:[0,1] op_sel_hi:[1,0] neg_lo:[0,1]
	v_pk_add_f32 v[22:23], v[16:17], v[20:21]
	v_pk_add_f32 v[16:17], v[16:17], v[20:21] neg_lo:[0,1] neg_hi:[0,1]
	v_pk_add_f32 v[20:21], v[30:31], v[10:11]
	v_pk_add_f32 v[10:11], v[30:31], v[10:11] neg_lo:[0,1] neg_hi:[0,1]
	v_pk_add_f32 v[30:31], v[8:9], v[12:13]
	v_pk_add_f32 v[8:9], v[8:9], v[12:13] neg_lo:[0,1] neg_hi:[0,1]
	v_pk_add_f32 v[12:13], v[0:1], v[4:5] op_sel:[0,1] op_sel_hi:[1,0] neg_hi:[0,1]
	v_pk_add_f32 v[0:1], v[0:1], v[4:5] op_sel:[0,1] op_sel_hi:[1,0] neg_lo:[0,1]
	v_pk_add_f32 v[4:5], v[2:3], v[6:7]
	v_pk_add_f32 v[2:3], v[2:3], v[6:7] neg_lo:[0,1] neg_hi:[0,1]
	s_nop 0
	v_pk_mul_f32 v[2:3], v[2:3], s[22:23]
	v_pk_add_f32 v[6:7], v[14:15], v[26:27]
	v_pk_add_f32 v[14:15], v[14:15], v[26:27] neg_lo:[0,1] neg_hi:[0,1]
	v_pk_add_f32 v[26:27], v[24:25], v[28:29] op_sel:[0,1] op_sel_hi:[1,0] neg_hi:[0,1]
	v_pk_add_f32 v[24:25], v[24:25], v[28:29] op_sel:[0,1] op_sel_hi:[1,0] neg_lo:[0,1]
	v_pk_add_f32 v[28:29], v[82:83], v[22:23]
	v_pk_add_f32 v[22:23], v[82:83], v[22:23] neg_lo:[0,1] neg_hi:[0,1]
	v_pk_add_f32 v[82:83], v[18:19], v[16:17] op_sel:[0,1] op_sel_hi:[1,0] neg_hi:[0,1]
	v_pk_add_f32 v[16:17], v[18:19], v[16:17] op_sel:[0,1] op_sel_hi:[1,0] neg_lo:[0,1]
	v_pk_add_f32 v[18:19], v[20:21], v[30:31]
	v_pk_add_f32 v[20:21], v[20:21], v[30:31] neg_lo:[0,1] neg_hi:[0,1]
	v_pk_add_f32 v[30:31], v[10:11], v[8:9] op_sel:[0,1] op_sel_hi:[1,0] neg_hi:[0,1]
	v_pk_add_f32 v[8:9], v[10:11], v[8:9] op_sel:[0,1] op_sel_hi:[1,0] neg_lo:[0,1]
	v_pk_add_f32 v[10:11], v[12:13], v[4:5]
	v_pk_add_f32 v[4:5], v[12:13], v[4:5] neg_lo:[0,1] neg_hi:[0,1]
	v_pk_add_f32 v[12:13], v[0:1], v[2:3] op_sel:[0,1] op_sel_hi:[1,0]
	v_pk_add_f32 v[0:1], v[0:1], v[2:3] op_sel:[0,1] op_sel_hi:[1,0] neg_lo:[0,1] neg_hi:[0,1]
	v_lshlrev_b32_e32 v2, 4, v37
	v_and_or_b32 v2, v2, s15, v47
	v_ashrrev_i32_e32 v3, 4, v2
	v_lshlrev_b32_e32 v3, 3, v3
	v_lshlrev_b32_e32 v2, 3, v2
	v_add3_u32 v2, 0, v3, v2
	ds_write_b64 v2, v[6:7]
	ds_write_b64 v2, v[14:15] offset:34816
	ds_write_b64 v2, v[26:27] offset:17408
	ds_write_b64 v2, v[24:25] offset:52224
	ds_write_b64 v2, v[28:29] offset:8704
	ds_write_b64 v2, v[22:23] offset:43520
	ds_write_b64 v2, v[82:83] offset:26112
	ds_write_b64 v2, v[16:17] offset:60928
	ds_write_b64 v2, v[18:19] offset:4352
	ds_write_b64 v2, v[20:21] offset:39168
	ds_write_b64 v2, v[30:31] offset:21760
	ds_write_b64 v2, v[8:9] offset:56576
	ds_write_b64 v2, v[10:11] offset:13056
	ds_write_b64 v2, v[4:5] offset:47872
	ds_write_b64 v2, v[12:13] offset:30464
	ds_write_b64 v2, v[0:1] offset:65280
	s_waitcnt lgkmcnt(0)
	s_barrier
	s_and_saveexec_b64 s[0:1], s[42:43]
	s_cbranch_execz .LBB0_500
	v_lshl_add_u64 v[2:3], v[78:79], 0, v[172:173]
	s_mov_b64 s[4:5], 0x80000
	v_lshl_add_u64 v[0:1], v[2:3], 0, s[4:5]
	v_add_co_u32_e32 v2, vcc, 0x80000, v2
	v_cmp_ne_u32_e64 s[42:43], 0, v39
	s_nop 0
	v_addc_co_u32_e32 v3, vcc, 0, v3, vcc
	global_load_dwordx4 v[12:15], v[2:3], off
	global_load_dwordx4 v[8:11], v[0:1], off offset:16
	v_mov_b32_e32 v19, 0
	v_mov_b32_e32 v21, 0
	v_mov_b32_e32 v33, 0
	s_and_saveexec_b64 s[4:5], s[42:43]
	s_cbranch_execz .LBB0_493
	global_load_ushort v33, v[0:1], off offset:-2

.LBB0_623:
	s_or_b64 exec, exec, s[4:5]
	v_mov_b32_e32 v41, v32
	s_waitcnt lgkmcnt(0)
	s_barrier
	s_add_u32 s100, s38, 0x400000
	s_addc_u32 s101, s39, 0
	v_lshl_add_u64 v[224:225], v[48:49], 1, s[100:101]
	global_load_dword v226, v[224:225], off
	s_add_u32 s100, s38, 0x1000000
	s_addc_u32 s101, s39, 0
	v_lshl_add_u64 v[228:229], v[48:49], 1, s[100:101]
	global_load_dword v226, v[228:229], off
	s_mov_b32 s11, s14
	v_and_b32_e32 v98, 31, v41
	v_cvt_f32_ubyte0_e32 v24, v98
	v_mul_f32_e32 v92, 0x3b000000, v24
	v_sin_f32_e32 v24, v92
	v_ashrrev_i32_e32 v0, 4, v41
	v_lshlrev_b32_e32 v0, 3, v0
	v_lshlrev_b32_e32 v1, 3, v41
	v_cos_f32_e32 v92, v92
	v_add3_u32 v25, 0, v0, v1
	ds_read_b64 v[0:1], v25
	ds_read_b64 v[2:3], v25 offset:4352
	ds_read_b64 v[4:5], v25 offset:8704
	ds_read_b64 v[6:7], v25 offset:13056
	ds_read_b64 v[8:9], v25 offset:17408
	ds_read_b64 v[10:11], v25 offset:21760
	ds_read_b64 v[12:13], v25 offset:26112
	ds_read_b64 v[14:15], v25 offset:30464
	ds_read_b64 v[16:17], v25 offset:34816
	ds_read_b64 v[18:19], v25 offset:39168
	ds_read_b64 v[20:21], v25 offset:43520
	ds_read_b64 v[22:23], v25 offset:47872
	v_xor_b32_e32 v93, 0x80000000, v24
	s_waitcnt lgkmcnt(10)
	v_pk_mul_f32 v[94:95], v[2:3], v[24:25] op_sel:[1,0] op_sel_hi:[0,0] neg_hi:[0,1]
	v_pk_fma_f32 v[2:3], v[2:3], v[92:93], v[94:95] op_sel_hi:[1,0,1]
	v_pk_mul_f32 v[94:95], v[24:25], v[92:93] op_sel:[0,1] op_sel_hi:[0,0] neg_hi:[1,0]
	v_pk_fma_f32 v[94:95], v[92:93], v[92:93], v[94:95] op_sel_hi:[0,1,1]
	ds_read_b64 v[26:27], v25 offset:52224
	ds_read_b64 v[28:29], v25 offset:56576
	ds_read_b64 v[30:31], v25 offset:60928
	ds_read_b64 v[86:87], v25 offset:65280
	s_waitcnt lgkmcnt(13)
	v_pk_mul_f32 v[96:97], v[4:5], v[94:95] op_sel:[1,1] op_sel_hi:[0,1] neg_lo:[0,1]
	v_pk_fma_f32 v[4:5], v[4:5], v[94:95], v[96:97] op_sel_hi:[1,0,1]
	v_pk_mul_f32 v[96:97], v[24:25], v[94:95] op_sel:[0,1] op_sel_hi:[0,0] neg_hi:[1,0]
	v_pk_fma_f32 v[94:95], v[92:93], v[94:95], v[96:97] op_sel_hi:[0,1,1]
	s_mov_b32 s35, s30
	s_waitcnt lgkmcnt(12)
	v_pk_mul_f32 v[96:97], v[6:7], v[94:95] op_sel:[1,1] op_sel_hi:[0,1] neg_lo:[0,1]
	v_pk_fma_f32 v[6:7], v[6:7], v[94:95], v[96:97] op_sel_hi:[1,0,1]
	v_pk_mul_f32 v[96:97], v[24:25], v[94:95] op_sel:[0,1] op_sel_hi:[0,0] neg_hi:[1,0]
	v_pk_fma_f32 v[94:95], v[92:93], v[94:95], v[96:97] op_sel_hi:[0,1,1]
	s_mov_b32 s26, s19
	s_waitcnt lgkmcnt(11)
	v_pk_mul_f32 v[96:97], v[8:9], v[94:95] op_sel:[1,1] op_sel_hi:[0,1] neg_lo:[0,1]
	v_pk_fma_f32 v[8:9], v[8:9], v[94:95], v[96:97] op_sel_hi:[1,0,1]
	v_pk_mul_f32 v[96:97], v[24:25], v[94:95] op_sel:[0,1] op_sel_hi:[0,0] neg_hi:[1,0]
	v_pk_fma_f32 v[94:95], v[92:93], v[94:95], v[96:97] op_sel_hi:[0,1,1]
	s_waitcnt lgkmcnt(0)
	v_pk_mul_f32 v[96:97], v[10:11], v[94:95] op_sel:[1,1] op_sel_hi:[0,1] neg_lo:[0,1]
	v_pk_fma_f32 v[10:11], v[10:11], v[94:95], v[96:97] op_sel_hi:[1,0,1]
	v_pk_mul_f32 v[96:97], v[24:25], v[94:95] op_sel:[0,1] op_sel_hi:[0,0] neg_hi:[1,0]
	v_pk_fma_f32 v[94:95], v[92:93], v[94:95], v[96:97] op_sel_hi:[0,1,1]
	s_barrier
	v_pk_mul_f32 v[96:97], v[12:13], v[94:95] op_sel:[1,1] op_sel_hi:[0,1] neg_lo:[0,1]
	v_pk_fma_f32 v[12:13], v[12:13], v[94:95], v[96:97] op_sel_hi:[1,0,1]
	v_pk_mul_f32 v[96:97], v[24:25], v[94:95] op_sel:[0,1] op_sel_hi:[0,0] neg_hi:[1,0]
	v_pk_fma_f32 v[94:95], v[92:93], v[94:95], v[96:97] op_sel_hi:[0,1,1]
	s_nop 0
	v_pk_mul_f32 v[96:97], v[14:15], v[94:95] op_sel:[1,1] op_sel_hi:[0,1] neg_lo:[0,1]
	v_pk_fma_f32 v[14:15], v[14:15], v[94:95], v[96:97] op_sel_hi:[1,0,1]
	v_pk_mul_f32 v[96:97], v[24:25], v[94:95] op_sel:[0,1] op_sel_hi:[0,0] neg_hi:[1,0]
	v_pk_fma_f32 v[94:95], v[92:93], v[94:95], v[96:97] op_sel_hi:[0,1,1]
	s_nop 0
	v_pk_mul_f32 v[96:97], v[16:17], v[94:95] op_sel:[1,1] op_sel_hi:[0,1] neg_lo:[0,1]
	v_pk_fma_f32 v[16:17], v[16:17], v[94:95], v[96:97] op_sel_hi:[1,0,1]
	v_pk_mul_f32 v[96:97], v[24:25], v[94:95] op_sel:[0,1] op_sel_hi:[0,0] neg_hi:[1,0]
	v_pk_fma_f32 v[94:95], v[92:93], v[94:95], v[96:97] op_sel_hi:[0,1,1]
	s_nop 0
	v_pk_mul_f32 v[96:97], v[18:19], v[94:95] op_sel:[1,1] op_sel_hi:[0,1] neg_lo:[0,1]
	v_pk_fma_f32 v[18:19], v[18:19], v[94:95], v[96:97] op_sel_hi:[1,0,1]
	v_pk_mul_f32 v[96:97], v[24:25], v[94:95] op_sel:[0,1] op_sel_hi:[0,0] neg_hi:[1,0]
	v_pk_fma_f32 v[94:95], v[92:93], v[94:95], v[96:97] op_sel_hi:[0,1,1]
	s_nop 0
	v_pk_mul_f32 v[96:97], v[20:21], v[94:95] op_sel:[1,1] op_sel_hi:[0,1] neg_lo:[0,1]
	v_pk_fma_f32 v[20:21], v[20:21], v[94:95], v[96:97] op_sel_hi:[1,0,1]
	v_pk_mul_f32 v[96:97], v[24:25], v[94:95] op_sel:[0,1] op_sel_hi:[0,0] neg_hi:[1,0]
	v_pk_fma_f32 v[94:95], v[92:93], v[94:95], v[96:97] op_sel_hi:[0,1,1]
	s_nop 0
	v_pk_mul_f32 v[96:97], v[22:23], v[94:95] op_sel:[1,1] op_sel_hi:[0,1] neg_lo:[0,1]
	v_pk_fma_f32 v[22:23], v[22:23], v[94:95], v[96:97] op_sel_hi:[1,0,1]
	v_pk_mul_f32 v[96:97], v[24:25], v[94:95] op_sel:[0,1] op_sel_hi:[0,0] neg_hi:[1,0]
	v_pk_fma_f32 v[94:95], v[92:93], v[94:95], v[96:97] op_sel_hi:[0,1,1]
	s_nop 0
	v_pk_mul_f32 v[96:97], v[26:27], v[94:95] op_sel:[1,1] op_sel_hi:[0,1] neg_lo:[0,1]
	v_pk_fma_f32 v[26:27], v[26:27], v[94:95], v[96:97] op_sel_hi:[1,0,1]
	v_pk_mul_f32 v[96:97], v[24:25], v[94:95] op_sel:[0,1] op_sel_hi:[0,0] neg_hi:[1,0]
	v_pk_fma_f32 v[94:95], v[92:93], v[94:95], v[96:97] op_sel_hi:[0,1,1]
	s_nop 0
	v_pk_mul_f32 v[96:97], v[28:29], v[94:95] op_sel:[1,1] op_sel_hi:[0,1] neg_lo:[0,1]
	v_pk_fma_f32 v[28:29], v[28:29], v[94:95], v[96:97] op_sel_hi:[1,0,1]
	v_pk_mul_f32 v[96:97], v[24:25], v[94:95] op_sel:[0,1] op_sel_hi:[0,0] neg_hi:[1,0]
	v_pk_fma_f32 v[94:95], v[92:93], v[94:95], v[96:97] op_sel_hi:[0,1,1]
	v_pk_mul_f32 v[24:25], v[24:25], v[94:95] op_sel:[0,1] op_sel_hi:[0,0] neg_hi:[1,0]
	v_pk_fma_f32 v[24:25], v[92:93], v[94:95], v[24:25] op_sel_hi:[0,1,1]
	v_pk_mul_f32 v[92:93], v[86:87], v[24:25] op_sel:[1,1] op_sel_hi:[0,1] neg_lo:[0,1]
	v_pk_fma_f32 v[24:25], v[86:87], v[24:25], v[92:93] op_sel_hi:[1,0,1]
	v_pk_add_f32 v[86:87], v[0:1], v[16:17]
	v_pk_add_f32 v[0:1], v[0:1], v[16:17] neg_lo:[0,1] neg_hi:[0,1]
	v_pk_add_f32 v[16:17], v[2:3], v[18:19]
	v_pk_add_f32 v[2:3], v[2:3], v[18:19] neg_lo:[0,1] neg_hi:[0,1]
	v_pk_mul_f32 v[96:97], v[30:31], v[94:95] op_sel:[1,1] op_sel_hi:[0,1] neg_lo:[0,1]
	v_pk_mul_f32 v[18:19], v[2:3], s[18:19]
	v_pk_fma_f32 v[30:31], v[30:31], v[94:95], v[96:97] op_sel_hi:[1,0,1]
	v_pk_fma_f32 v[2:3], v[2:3], s[30:31], v[18:19] op_sel:[0,0,1] op_sel_hi:[1,0,0]
	v_pk_add_f32 v[18:19], v[4:5], v[20:21]
	v_pk_add_f32 v[4:5], v[4:5], v[20:21] neg_lo:[0,1] neg_hi:[0,1]
	s_nop 0
	v_pk_mul_f32 v[20:21], v[4:5], s[10:11]
	s_nop 0
	v_pk_fma_f32 v[4:5], v[4:5], s[14:15], v[20:21] op_sel:[0,0,1] op_sel_hi:[1,0,0]
	v_pk_add_f32 v[20:21], v[6:7], v[22:23]
	v_pk_add_f32 v[6:7], v[6:7], v[22:23] neg_lo:[0,1] neg_hi:[0,1]
	s_nop 0
	v_pk_mul_f32 v[22:23], v[6:7], s[34:35]
	s_nop 0
	v_pk_fma_f32 v[6:7], v[6:7], s[26:27], v[22:23] op_sel:[0,0,1] op_sel_hi:[1,0,0]
	v_pk_add_f32 v[22:23], v[8:9], v[26:27]
	v_pk_add_f32 v[8:9], v[8:9], v[26:27] neg_lo:[0,1] neg_hi:[0,1]
	v_pk_add_f32 v[26:27], v[10:11], v[28:29]
	v_pk_add_f32 v[10:11], v[10:11], v[28:29] neg_lo:[0,1] neg_hi:[0,1]
	s_nop 0
	v_pk_mul_f32 v[28:29], v[10:11], s[34:35]
	s_nop 0
	v_pk_fma_f32 v[10:11], v[10:11], s[26:27], v[28:29] op_sel:[0,0,1] op_sel_hi:[1,0,0] neg_lo:[1,0,0] neg_hi:[1,0,0]
	v_pk_add_f32 v[28:29], v[12:13], v[30:31]
	v_pk_add_f32 v[12:13], v[12:13], v[30:31] neg_lo:[0,1] neg_hi:[0,1]
	s_nop 0
	v_pk_mul_f32 v[30:31], v[12:13], s[10:11]
	s_nop 0
	v_pk_fma_f32 v[12:13], v[12:13], s[14:15], v[30:31] op_sel:[0,0,1] op_sel_hi:[1,0,0] neg_lo:[1,0,0] neg_hi:[1,0,0]
	v_pk_add_f32 v[30:31], v[14:15], v[24:25]
	v_pk_add_f32 v[14:15], v[14:15], v[24:25] neg_lo:[0,1] neg_hi:[0,1]
	s_nop 0
	v_pk_mul_f32 v[24:25], v[14:15], s[18:19]
	s_nop 0
	v_pk_fma_f32 v[14:15], v[14:15], s[30:31], v[24:25] op_sel:[0,0,1] op_sel_hi:[1,0,0] neg_lo:[1,0,0] neg_hi:[1,0,0]
	v_pk_add_f32 v[24:25], v[86:87], v[22:23]
	v_pk_add_f32 v[22:23], v[86:87], v[22:23] neg_lo:[0,1] neg_hi:[0,1]
	v_pk_add_f32 v[86:87], v[16:17], v[26:27]
	v_pk_add_f32 v[16:17], v[16:17], v[26:27] neg_lo:[0,1] neg_hi:[0,1]
	s_nop 0
	v_pk_mul_f32 v[26:27], v[16:17], s[10:11]
	s_nop 0
	v_pk_fma_f32 v[16:17], v[16:17], s[14:15], v[26:27] op_sel:[0,0,1] op_sel_hi:[1,0,0]
	v_pk_add_f32 v[26:27], v[18:19], v[28:29]
	v_pk_add_f32 v[18:19], v[18:19], v[28:29] neg_lo:[0,1] neg_hi:[0,1]
	v_pk_add_f32 v[28:29], v[20:21], v[30:31]
	v_pk_add_f32 v[20:21], v[20:21], v[30:31] neg_lo:[0,1] neg_hi:[0,1]
	s_nop 0
	v_pk_mul_f32 v[30:31], v[20:21], s[10:11]
	s_nop 0
	v_pk_fma_f32 v[20:21], v[20:21], s[14:15], v[30:31] op_sel:[0,0,1] op_sel_hi:[1,0,0] neg_lo:[1,0,0] neg_hi:[1,0,0]
	v_pk_add_f32 v[30:31], v[0:1], v[8:9] op_sel:[0,1] op_sel_hi:[1,0] neg_hi:[0,1]
	v_pk_add_f32 v[0:1], v[0:1], v[8:9] op_sel:[0,1] op_sel_hi:[1,0] neg_lo:[0,1]
	v_pk_add_f32 v[8:9], v[2:3], v[10:11]
	v_pk_add_f32 v[2:3], v[2:3], v[10:11] neg_lo:[0,1] neg_hi:[0,1]
	s_nop 0
	v_pk_mul_f32 v[10:11], v[2:3], s[10:11]
	s_nop 0
	v_pk_fma_f32 v[2:3], v[2:3], s[14:15], v[10:11] op_sel:[0,0,1] op_sel_hi:[1,0,0]
	v_pk_add_f32 v[10:11], v[4:5], v[12:13]
	v_pk_add_f32 v[4:5], v[4:5], v[12:13] neg_lo:[0,1] neg_hi:[0,1]
	v_pk_add_f32 v[12:13], v[6:7], v[14:15]
	v_pk_add_f32 v[6:7], v[6:7], v[14:15] neg_lo:[0,1] neg_hi:[0,1]
	s_nop 0
	v_pk_mul_f32 v[14:15], v[6:7], s[10:11]
	s_nop 0
	v_pk_fma_f32 v[6:7], v[6:7], s[14:15], v[14:15] op_sel:[0,0,1] op_sel_hi:[1,0,0] neg_lo:[1,0,0] neg_hi:[1,0,0]
	v_pk_add_f32 v[14:15], v[24:25], v[26:27]
	v_pk_add_f32 v[24:25], v[24:25], v[26:27] neg_lo:[0,1] neg_hi:[0,1]
	v_pk_add_f32 v[26:27], v[86:87], v[28:29]
	v_pk_add_f32 v[28:29], v[86:87], v[28:29] neg_lo:[0,1] neg_hi:[0,1]
	v_pk_add_f32 v[86:87], v[22:23], v[18:19] op_sel:[0,1] op_sel_hi:[1,0] neg_hi:[0,1]
	v_pk_add_f32 v[18:19], v[22:23], v[18:19] op_sel:[0,1] op_sel_hi:[1,0] neg_lo:[0,1]
	v_pk_add_f32 v[22:23], v[16:17], v[20:21]
	v_pk_add_f32 v[16:17], v[16:17], v[20:21] neg_lo:[0,1] neg_hi:[0,1]
	v_pk_add_f32 v[20:21], v[30:31], v[10:11]
	v_pk_add_f32 v[10:11], v[30:31], v[10:11] neg_lo:[0,1] neg_hi:[0,1]
	v_pk_add_f32 v[30:31], v[8:9], v[12:13]
	v_pk_add_f32 v[8:9], v[8:9], v[12:13] neg_lo:[0,1] neg_hi:[0,1]
	v_pk_add_f32 v[12:13], v[0:1], v[4:5] op_sel:[0,1] op_sel_hi:[1,0] neg_hi:[0,1]
	v_pk_add_f32 v[0:1], v[0:1], v[4:5] op_sel:[0,1] op_sel_hi:[1,0] neg_lo:[0,1]
	v_pk_add_f32 v[4:5], v[2:3], v[6:7]
	v_pk_add_f32 v[2:3], v[2:3], v[6:7] neg_lo:[0,1] neg_hi:[0,1]
	s_nop 0
	v_pk_mul_f32 v[2:3], v[2:3], s[22:23]
	v_pk_add_f32 v[6:7], v[14:15], v[26:27]
	v_pk_add_f32 v[14:15], v[14:15], v[26:27] neg_lo:[0,1] neg_hi:[0,1]
	v_pk_add_f32 v[26:27], v[24:25], v[28:29] op_sel:[0,1] op_sel_hi:[1,0] neg_hi:[0,1]
	v_pk_add_f32 v[24:25], v[24:25], v[28:29] op_sel:[0,1] op_sel_hi:[1,0] neg_lo:[0,1]
	v_pk_add_f32 v[28:29], v[86:87], v[22:23]
	v_pk_add_f32 v[22:23], v[86:87], v[22:23] neg_lo:[0,1] neg_hi:[0,1]
	v_pk_add_f32 v[86:87], v[18:19], v[16:17] op_sel:[0,1] op_sel_hi:[1,0] neg_hi:[0,1]
	v_pk_add_f32 v[16:17], v[18:19], v[16:17] op_sel:[0,1] op_sel_hi:[1,0] neg_lo:[0,1]
	v_pk_add_f32 v[18:19], v[20:21], v[30:31]
	v_pk_add_f32 v[20:21], v[20:21], v[30:31] neg_lo:[0,1] neg_hi:[0,1]
	v_pk_add_f32 v[30:31], v[10:11], v[8:9] op_sel:[0,1] op_sel_hi:[1,0] neg_hi:[0,1]
	v_pk_add_f32 v[8:9], v[10:11], v[8:9] op_sel:[0,1] op_sel_hi:[1,0] neg_lo:[0,1]
	v_pk_add_f32 v[10:11], v[12:13], v[4:5]
	v_pk_add_f32 v[4:5], v[12:13], v[4:5] neg_lo:[0,1] neg_hi:[0,1]
	v_pk_add_f32 v[12:13], v[0:1], v[2:3] op_sel:[0,1] op_sel_hi:[1,0]
	v_pk_add_f32 v[0:1], v[0:1], v[2:3] op_sel:[0,1] op_sel_hi:[1,0] neg_lo:[0,1] neg_hi:[0,1]
	v_lshlrev_b32_e32 v2, 4, v41
	v_and_or_b32 v2, v2, s7, v98
	v_ashrrev_i32_e32 v3, 4, v2
	v_lshlrev_b32_e32 v3, 3, v3
	v_lshlrev_b32_e32 v2, 3, v2
	v_add3_u32 v2, 0, v3, v2
	v_add_u32_e32 v3, 0x800, v2
	v_mov_b32_e32 v41, v32
	ds_write2_b64 v2, v[6:7], v[18:19] offset1:34
	ds_write2_b64 v3, v[14:15], v[20:21] offset0:16 offset1:50
	ds_write2_b64 v2, v[26:27], v[30:31] offset0:136 offset1:170
	ds_write2_b64 v3, v[24:25], v[8:9] offset0:152 offset1:186
	ds_write2_b64 v2, v[28:29], v[10:11] offset0:68 offset1:102
	ds_write2_b64 v3, v[22:23], v[4:5] offset0:84 offset1:118
	ds_write2_b64 v2, v[86:87], v[12:13] offset0:204 offset1:238
	ds_write2_b64 v3, v[16:17], v[0:1] offset0:220 offset1:254
	s_waitcnt lgkmcnt(0)
	s_barrier
	s_nop 0
	v_and_b32_e32 v98, 0x1ff, v41
	v_cvt_f32_u32_e32 v24, v98
	v_ashrrev_i32_e32 v0, 4, v41
	v_lshlrev_b32_e32 v0, 3, v0
	v_lshlrev_b32_e32 v1, 3, v41
	v_mul_f32_e32 v92, 0x39000000, v24
	v_sin_f32_e32 v24, v92
	v_cos_f32_e32 v92, v92
	v_add3_u32 v25, 0, v0, v1
	ds_read_b64 v[0:1], v25
	ds_read_b64 v[2:3], v25 offset:4352
	ds_read_b64 v[4:5], v25 offset:8704
	ds_read_b64 v[6:7], v25 offset:13056
	ds_read_b64 v[8:9], v25 offset:17408
	ds_read_b64 v[10:11], v25 offset:21760
	ds_read_b64 v[12:13], v25 offset:26112
	ds_read_b64 v[14:15], v25 offset:30464
	v_xor_b32_e32 v93, 0x80000000, v24
	s_waitcnt lgkmcnt(6)
	v_pk_mul_f32 v[94:95], v[2:3], v[24:25] op_sel:[1,0] op_sel_hi:[0,0] neg_hi:[0,1]
	v_pk_fma_f32 v[2:3], v[2:3], v[92:93], v[94:95] op_sel_hi:[1,0,1]
	v_pk_mul_f32 v[94:95], v[24:25], v[92:93] op_sel:[0,1] op_sel_hi:[0,0] neg_hi:[1,0]
	v_pk_fma_f32 v[94:95], v[92:93], v[92:93], v[94:95] op_sel_hi:[0,1,1]
	ds_read_b64 v[16:17], v25 offset:34816
	ds_read_b64 v[18:19], v25 offset:39168
	ds_read_b64 v[20:21], v25 offset:43520
	ds_read_b64 v[22:23], v25 offset:47872
	s_waitcnt lgkmcnt(9)
	v_pk_mul_f32 v[96:97], v[4:5], v[94:95] op_sel:[1,1] op_sel_hi:[0,1] neg_lo:[0,1]
	v_pk_fma_f32 v[4:5], v[4:5], v[94:95], v[96:97] op_sel_hi:[1,0,1]
	v_pk_mul_f32 v[96:97], v[24:25], v[94:95] op_sel:[0,1] op_sel_hi:[0,0] neg_hi:[1,0]
	v_pk_fma_f32 v[94:95], v[92:93], v[94:95], v[96:97] op_sel_hi:[0,1,1]
	ds_read_b64 v[26:27], v25 offset:52224
	ds_read_b64 v[28:29], v25 offset:56576
	ds_read_b64 v[30:31], v25 offset:60928
	ds_read_b64 v[86:87], v25 offset:65280
	s_waitcnt lgkmcnt(12)
	v_pk_mul_f32 v[96:97], v[6:7], v[94:95] op_sel:[1,1] op_sel_hi:[0,1] neg_lo:[0,1]
	v_pk_fma_f32 v[6:7], v[6:7], v[94:95], v[96:97] op_sel_hi:[1,0,1]
	v_pk_mul_f32 v[96:97], v[24:25], v[94:95] op_sel:[0,1] op_sel_hi:[0,0] neg_hi:[1,0]
	v_pk_fma_f32 v[94:95], v[92:93], v[94:95], v[96:97] op_sel_hi:[0,1,1]
	s_waitcnt lgkmcnt(0)
	v_pk_mul_f32 v[96:97], v[8:9], v[94:95] op_sel:[1,1] op_sel_hi:[0,1] neg_lo:[0,1]
	v_pk_fma_f32 v[8:9], v[8:9], v[94:95], v[96:97] op_sel_hi:[1,0,1]
	v_pk_mul_f32 v[96:97], v[24:25], v[94:95] op_sel:[0,1] op_sel_hi:[0,0] neg_hi:[1,0]
	v_pk_fma_f32 v[94:95], v[92:93], v[94:95], v[96:97] op_sel_hi:[0,1,1]
	s_barrier
	v_pk_mul_f32 v[96:97], v[10:11], v[94:95] op_sel:[1,1] op_sel_hi:[0,1] neg_lo:[0,1]
	v_pk_fma_f32 v[10:11], v[10:11], v[94:95], v[96:97] op_sel_hi:[1,0,1]
	v_pk_mul_f32 v[96:97], v[24:25], v[94:95] op_sel:[0,1] op_sel_hi:[0,0] neg_hi:[1,0]
	v_pk_fma_f32 v[94:95], v[92:93], v[94:95], v[96:97] op_sel_hi:[0,1,1]
	s_nop 0
	v_pk_mul_f32 v[96:97], v[12:13], v[94:95] op_sel:[1,1] op_sel_hi:[0,1] neg_lo:[0,1]
	v_pk_fma_f32 v[12:13], v[12:13], v[94:95], v[96:97] op_sel_hi:[1,0,1]
	v_pk_mul_f32 v[96:97], v[24:25], v[94:95] op_sel:[0,1] op_sel_hi:[0,0] neg_hi:[1,0]
	v_pk_fma_f32 v[94:95], v[92:93], v[94:95], v[96:97] op_sel_hi:[0,1,1]
	s_nop 0
	v_pk_mul_f32 v[96:97], v[14:15], v[94:95] op_sel:[1,1] op_sel_hi:[0,1] neg_lo:[0,1]
	v_pk_fma_f32 v[14:15], v[14:15], v[94:95], v[96:97] op_sel_hi:[1,0,1]
	v_pk_mul_f32 v[96:97], v[24:25], v[94:95] op_sel:[0,1] op_sel_hi:[0,0] neg_hi:[1,0]
	v_pk_fma_f32 v[94:95], v[92:93], v[94:95], v[96:97] op_sel_hi:[0,1,1]
	s_nop 0
	v_pk_mul_f32 v[96:97], v[16:17], v[94:95] op_sel:[1,1] op_sel_hi:[0,1] neg_lo:[0,1]
	v_pk_fma_f32 v[16:17], v[16:17], v[94:95], v[96:97] op_sel_hi:[1,0,1]
	v_pk_mul_f32 v[96:97], v[24:25], v[94:95] op_sel:[0,1] op_sel_hi:[0,0] neg_hi:[1,0]
	v_pk_fma_f32 v[94:95], v[92:93], v[94:95], v[96:97] op_sel_hi:[0,1,1]
	s_nop 0
	v_pk_mul_f32 v[96:97], v[18:19], v[94:95] op_sel:[1,1] op_sel_hi:[0,1] neg_lo:[0,1]
	v_pk_fma_f32 v[18:19], v[18:19], v[94:95], v[96:97] op_sel_hi:[1,0,1]
	v_pk_mul_f32 v[96:97], v[24:25], v[94:95] op_sel:[0,1] op_sel_hi:[0,0] neg_hi:[1,0]
	v_pk_fma_f32 v[94:95], v[92:93], v[94:95], v[96:97] op_sel_hi:[0,1,1]
	s_nop 0
	v_pk_mul_f32 v[96:97], v[20:21], v[94:95] op_sel:[1,1] op_sel_hi:[0,1] neg_lo:[0,1]
	v_pk_fma_f32 v[20:21], v[20:21], v[94:95], v[96:97] op_sel_hi:[1,0,1]
	v_pk_mul_f32 v[96:97], v[24:25], v[94:95] op_sel:[0,1] op_sel_hi:[0,0] neg_hi:[1,0]
	v_pk_fma_f32 v[94:95], v[92:93], v[94:95], v[96:97] op_sel_hi:[0,1,1]
	s_nop 0
	v_pk_mul_f32 v[96:97], v[22:23], v[94:95] op_sel:[1,1] op_sel_hi:[0,1] neg_lo:[0,1]
	v_pk_fma_f32 v[22:23], v[22:23], v[94:95], v[96:97] op_sel_hi:[1,0,1]
	v_pk_mul_f32 v[96:97], v[24:25], v[94:95] op_sel:[0,1] op_sel_hi:[0,0] neg_hi:[1,0]
	v_pk_fma_f32 v[94:95], v[92:93], v[94:95], v[96:97] op_sel_hi:[0,1,1]
	s_nop 0
	v_pk_mul_f32 v[96:97], v[26:27], v[94:95] op_sel:[1,1] op_sel_hi:[0,1] neg_lo:[0,1]
	v_pk_fma_f32 v[26:27], v[26:27], v[94:95], v[96:97] op_sel_hi:[1,0,1]
	v_pk_mul_f32 v[96:97], v[24:25], v[94:95] op_sel:[0,1] op_sel_hi:[0,0] neg_hi:[1,0]
	v_pk_fma_f32 v[94:95], v[92:93], v[94:95], v[96:97] op_sel_hi:[0,1,1]
	s_nop 0
	v_pk_mul_f32 v[96:97], v[28:29], v[94:95] op_sel:[1,1] op_sel_hi:[0,1] neg_lo:[0,1]
	v_pk_fma_f32 v[28:29], v[28:29], v[94:95], v[96:97] op_sel_hi:[1,0,1]
	v_pk_mul_f32 v[96:97], v[24:25], v[94:95] op_sel:[0,1] op_sel_hi:[0,0] neg_hi:[1,0]
	v_pk_fma_f32 v[94:95], v[92:93], v[94:95], v[96:97] op_sel_hi:[0,1,1]
	v_pk_mul_f32 v[24:25], v[24:25], v[94:95] op_sel:[0,1] op_sel_hi:[0,0] neg_hi:[1,0]
	v_pk_fma_f32 v[24:25], v[92:93], v[94:95], v[24:25] op_sel_hi:[0,1,1]
	v_pk_mul_f32 v[92:93], v[86:87], v[24:25] op_sel:[1,1] op_sel_hi:[0,1] neg_lo:[0,1]
	v_pk_fma_f32 v[24:25], v[86:87], v[24:25], v[92:93] op_sel_hi:[1,0,1]
	v_pk_add_f32 v[86:87], v[0:1], v[16:17]
	v_pk_add_f32 v[0:1], v[0:1], v[16:17] neg_lo:[0,1] neg_hi:[0,1]
	v_pk_add_f32 v[16:17], v[2:3], v[18:19]
	v_pk_add_f32 v[2:3], v[2:3], v[18:19] neg_lo:[0,1] neg_hi:[0,1]
	v_pk_mul_f32 v[96:97], v[30:31], v[94:95] op_sel:[1,1] op_sel_hi:[0,1] neg_lo:[0,1]
	v_pk_mul_f32 v[18:19], v[2:3], s[18:19]
	v_pk_fma_f32 v[30:31], v[30:31], v[94:95], v[96:97] op_sel_hi:[1,0,1]
	v_pk_fma_f32 v[2:3], v[2:3], s[30:31], v[18:19] op_sel:[0,0,1] op_sel_hi:[1,0,0]
	v_pk_add_f32 v[18:19], v[4:5], v[20:21]
	v_pk_add_f32 v[4:5], v[4:5], v[20:21] neg_lo:[0,1] neg_hi:[0,1]
	s_nop 0
	v_pk_mul_f32 v[20:21], v[4:5], s[10:11]
	s_nop 0
	v_pk_fma_f32 v[4:5], v[4:5], s[14:15], v[20:21] op_sel:[0,0,1] op_sel_hi:[1,0,0]
	v_pk_add_f32 v[20:21], v[6:7], v[22:23]
	v_pk_add_f32 v[6:7], v[6:7], v[22:23] neg_lo:[0,1] neg_hi:[0,1]
	s_nop 0
	v_pk_mul_f32 v[22:23], v[6:7], s[34:35]
	s_nop 0
	v_pk_fma_f32 v[6:7], v[6:7], s[26:27], v[22:23] op_sel:[0,0,1] op_sel_hi:[1,0,0]
	v_pk_add_f32 v[22:23], v[8:9], v[26:27]
	v_pk_add_f32 v[8:9], v[8:9], v[26:27] neg_lo:[0,1] neg_hi:[0,1]
	v_pk_add_f32 v[26:27], v[10:11], v[28:29]
	v_pk_add_f32 v[10:11], v[10:11], v[28:29] neg_lo:[0,1] neg_hi:[0,1]
	s_nop 0
	v_pk_mul_f32 v[28:29], v[10:11], s[34:35]
	s_nop 0
	v_pk_fma_f32 v[10:11], v[10:11], s[26:27], v[28:29] op_sel:[0,0,1] op_sel_hi:[1,0,0] neg_lo:[1,0,0] neg_hi:[1,0,0]
	v_pk_add_f32 v[28:29], v[12:13], v[30:31]
	v_pk_add_f32 v[12:13], v[12:13], v[30:31] neg_lo:[0,1] neg_hi:[0,1]
	s_nop 0
	v_pk_mul_f32 v[30:31], v[12:13], s[10:11]
	s_nop 0
	v_pk_fma_f32 v[12:13], v[12:13], s[14:15], v[30:31] op_sel:[0,0,1] op_sel_hi:[1,0,0] neg_lo:[1,0,0] neg_hi:[1,0,0]
	v_pk_add_f32 v[30:31], v[14:15], v[24:25]
	v_pk_add_f32 v[14:15], v[14:15], v[24:25] neg_lo:[0,1] neg_hi:[0,1]
	s_nop 0
	v_pk_mul_f32 v[24:25], v[14:15], s[18:19]
	s_nop 0
	v_pk_fma_f32 v[14:15], v[14:15], s[30:31], v[24:25] op_sel:[0,0,1] op_sel_hi:[1,0,0] neg_lo:[1,0,0] neg_hi:[1,0,0]
	v_pk_add_f32 v[24:25], v[86:87], v[22:23]
	v_pk_add_f32 v[22:23], v[86:87], v[22:23] neg_lo:[0,1] neg_hi:[0,1]
	v_pk_add_f32 v[86:87], v[16:17], v[26:27]
	v_pk_add_f32 v[16:17], v[16:17], v[26:27] neg_lo:[0,1] neg_hi:[0,1]
	s_nop 0
	v_pk_mul_f32 v[26:27], v[16:17], s[10:11]
	s_nop 0
	v_pk_fma_f32 v[16:17], v[16:17], s[14:15], v[26:27] op_sel:[0,0,1] op_sel_hi:[1,0,0]
	v_pk_add_f32 v[26:27], v[18:19], v[28:29]
	v_pk_add_f32 v[18:19], v[18:19], v[28:29] neg_lo:[0,1] neg_hi:[0,1]
	v_pk_add_f32 v[28:29], v[20:21], v[30:31]
	v_pk_add_f32 v[20:21], v[20:21], v[30:31] neg_lo:[0,1] neg_hi:[0,1]
	s_nop 0
	v_pk_mul_f32 v[30:31], v[20:21], s[10:11]
	s_nop 0
	v_pk_fma_f32 v[20:21], v[20:21], s[14:15], v[30:31] op_sel:[0,0,1] op_sel_hi:[1,0,0] neg_lo:[1,0,0] neg_hi:[1,0,0]
	v_pk_add_f32 v[30:31], v[0:1], v[8:9] op_sel:[0,1] op_sel_hi:[1,0] neg_hi:[0,1]
	v_pk_add_f32 v[0:1], v[0:1], v[8:9] op_sel:[0,1] op_sel_hi:[1,0] neg_lo:[0,1]
	v_pk_add_f32 v[8:9], v[2:3], v[10:11]
	v_pk_add_f32 v[2:3], v[2:3], v[10:11] neg_lo:[0,1] neg_hi:[0,1]
	s_nop 0
	v_pk_mul_f32 v[10:11], v[2:3], s[10:11]
	s_nop 0
	v_pk_fma_f32 v[2:3], v[2:3], s[14:15], v[10:11] op_sel:[0,0,1] op_sel_hi:[1,0,0]
	v_pk_add_f32 v[10:11], v[4:5], v[12:13]
	v_pk_add_f32 v[4:5], v[4:5], v[12:13] neg_lo:[0,1] neg_hi:[0,1]
	v_pk_add_f32 v[12:13], v[6:7], v[14:15]
	v_pk_add_f32 v[6:7], v[6:7], v[14:15] neg_lo:[0,1] neg_hi:[0,1]
	s_nop 0
	v_pk_mul_f32 v[14:15], v[6:7], s[10:11]
	s_nop 0
	v_pk_fma_f32 v[6:7], v[6:7], s[14:15], v[14:15] op_sel:[0,0,1] op_sel_hi:[1,0,0] neg_lo:[1,0,0] neg_hi:[1,0,0]
	v_pk_add_f32 v[14:15], v[24:25], v[26:27]
	v_pk_add_f32 v[24:25], v[24:25], v[26:27] neg_lo:[0,1] neg_hi:[0,1]
	v_pk_add_f32 v[26:27], v[86:87], v[28:29]
	v_pk_add_f32 v[28:29], v[86:87], v[28:29] neg_lo:[0,1] neg_hi:[0,1]
	v_pk_add_f32 v[86:87], v[22:23], v[18:19] op_sel:[0,1] op_sel_hi:[1,0] neg_hi:[0,1]
	v_pk_add_f32 v[18:19], v[22:23], v[18:19] op_sel:[0,1] op_sel_hi:[1,0] neg_lo:[0,1]
	v_pk_add_f32 v[22:23], v[16:17], v[20:21]
	v_pk_add_f32 v[16:17], v[16:17], v[20:21] neg_lo:[0,1] neg_hi:[0,1]
	v_pk_add_f32 v[20:21], v[30:31], v[10:11]
	v_pk_add_f32 v[10:11], v[30:31], v[10:11] neg_lo:[0,1] neg_hi:[0,1]
	v_pk_add_f32 v[30:31], v[8:9], v[12:13]
	v_pk_add_f32 v[8:9], v[8:9], v[12:13] neg_lo:[0,1] neg_hi:[0,1]
	v_pk_add_f32 v[12:13], v[0:1], v[4:5] op_sel:[0,1] op_sel_hi:[1,0] neg_hi:[0,1]
	v_pk_add_f32 v[0:1], v[0:1], v[4:5] op_sel:[0,1] op_sel_hi:[1,0] neg_lo:[0,1]
	v_pk_add_f32 v[4:5], v[2:3], v[6:7]
	v_pk_add_f32 v[2:3], v[2:3], v[6:7] neg_lo:[0,1] neg_hi:[0,1]
	s_nop 0
	v_pk_mul_f32 v[2:3], v[2:3], s[22:23]
	v_pk_add_f32 v[6:7], v[14:15], v[26:27]
	v_pk_add_f32 v[14:15], v[14:15], v[26:27] neg_lo:[0,1] neg_hi:[0,1]
	v_pk_add_f32 v[26:27], v[24:25], v[28:29] op_sel:[0,1] op_sel_hi:[1,0] neg_hi:[0,1]
	v_pk_add_f32 v[24:25], v[24:25], v[28:29] op_sel:[0,1] op_sel_hi:[1,0] neg_lo:[0,1]
	v_pk_add_f32 v[28:29], v[86:87], v[22:23]
	v_pk_add_f32 v[22:23], v[86:87], v[22:23] neg_lo:[0,1] neg_hi:[0,1]
	v_pk_add_f32 v[86:87], v[18:19], v[16:17] op_sel:[0,1] op_sel_hi:[1,0] neg_hi:[0,1]
	v_pk_add_f32 v[16:17], v[18:19], v[16:17] op_sel:[0,1] op_sel_hi:[1,0] neg_lo:[0,1]
	v_pk_add_f32 v[18:19], v[20:21], v[30:31]
	v_pk_add_f32 v[20:21], v[20:21], v[30:31] neg_lo:[0,1] neg_hi:[0,1]
	v_pk_add_f32 v[30:31], v[10:11], v[8:9] op_sel:[0,1] op_sel_hi:[1,0] neg_hi:[0,1]
	v_pk_add_f32 v[8:9], v[10:11], v[8:9] op_sel:[0,1] op_sel_hi:[1,0] neg_lo:[0,1]
	v_pk_add_f32 v[10:11], v[12:13], v[4:5]
	v_pk_add_f32 v[4:5], v[12:13], v[4:5] neg_lo:[0,1] neg_hi:[0,1]
	v_pk_add_f32 v[12:13], v[0:1], v[2:3] op_sel:[0,1] op_sel_hi:[1,0]
	v_pk_add_f32 v[0:1], v[0:1], v[2:3] op_sel:[0,1] op_sel_hi:[1,0] neg_lo:[0,1] neg_hi:[0,1]
	v_lshlrev_b32_e32 v2, 4, v41
	v_and_or_b32 v2, v2, s15, v98
	v_ashrrev_i32_e32 v3, 4, v2
	v_lshlrev_b32_e32 v3, 3, v3
	v_lshlrev_b32_e32 v2, 3, v2
	v_add3_u32 v2, 0, v3, v2
	ds_write_b64 v2, v[6:7]
	ds_write_b64 v2, v[14:15] offset:34816
	ds_write_b64 v2, v[26:27] offset:17408
	ds_write_b64 v2, v[24:25] offset:52224
	ds_write_b64 v2, v[28:29] offset:8704
	ds_write_b64 v2, v[22:23] offset:43520
	ds_write_b64 v2, v[86:87] offset:26112
	ds_write_b64 v2, v[16:17] offset:60928
	ds_write_b64 v2, v[18:19] offset:4352
	ds_write_b64 v2, v[20:21] offset:39168
	ds_write_b64 v2, v[30:31] offset:21760
	ds_write_b64 v2, v[8:9] offset:56576
	ds_write_b64 v2, v[10:11] offset:13056
	ds_write_b64 v2, v[4:5] offset:47872
	ds_write_b64 v2, v[12:13] offset:30464
	ds_write_b64 v2, v[0:1] offset:65280
	s_waitcnt lgkmcnt(0)
	s_barrier
	s_and_saveexec_b64 s[28:29], s[40:41]
	s_cbranch_execz .LBB0_633
	s_add_u32 s4, s38, 0x400000
	s_addc_u32 s5, s39, 0
	v_lshl_add_u64 v[0:1], v[48:49], 1, s[4:5]
	global_load_dwordx4 v[8:11], v[0:1], off offset:16
	global_load_dwordx4 v[12:15], v[0:1], off
	v_mov_b32_e32 v19, 0
	v_mov_b32_e32 v18, 0
	v_mov_b32_e32 v86, 0
	s_and_saveexec_b64 s[8:9], s[42:43]
	s_cbranch_execz .LBB0_626
	v_lshl_add_u64 v[2:3], v[172:173], 1, s[4:5]
	global_load_ushort v86, v[2:3], off offset:-2

.LBB0_675:
	s_or_b64 exec, exec, s[4:5]
	v_mov_b32_e32 v41, v32
	s_waitcnt lgkmcnt(0)
	s_barrier
	s_add_u32 s100, s38, 0x800000
	s_addc_u32 s101, s39, 0
	v_lshl_add_u64 v[224:225], v[48:49], 1, s[100:101]
	global_load_dword v226, v[224:225], off
	s_add_u32 s100, s38, 0x1400000
	s_addc_u32 s101, s39, 0
	v_lshl_add_u64 v[228:229], v[48:49], 1, s[100:101]
	global_load_dword v226, v[228:229], off
	s_mov_b32 s11, s14
	v_and_b32_e32 v98, 31, v41
	v_cvt_f32_ubyte0_e32 v24, v98
	v_mul_f32_e32 v60, 0x3b000000, v24
	v_sin_f32_e32 v24, v60
	v_ashrrev_i32_e32 v0, 4, v41
	v_lshlrev_b32_e32 v0, 3, v0
	v_lshlrev_b32_e32 v1, 3, v41
	v_cos_f32_e32 v60, v60
	v_add3_u32 v25, 0, v0, v1
	ds_read_b64 v[0:1], v25
	ds_read_b64 v[2:3], v25 offset:4352
	ds_read_b64 v[4:5], v25 offset:8704
	ds_read_b64 v[6:7], v25 offset:13056
	ds_read_b64 v[8:9], v25 offset:17408
	ds_read_b64 v[10:11], v25 offset:21760
	ds_read_b64 v[12:13], v25 offset:26112
	ds_read_b64 v[14:15], v25 offset:30464
	ds_read_b64 v[16:17], v25 offset:34816
	ds_read_b64 v[18:19], v25 offset:39168
	ds_read_b64 v[20:21], v25 offset:43520
	ds_read_b64 v[22:23], v25 offset:47872
	v_xor_b32_e32 v61, 0x80000000, v24
	s_waitcnt lgkmcnt(10)
	v_pk_mul_f32 v[94:95], v[2:3], v[24:25] op_sel:[1,0] op_sel_hi:[0,0] neg_hi:[0,1]
	v_pk_fma_f32 v[2:3], v[2:3], v[60:61], v[94:95] op_sel_hi:[1,0,1]
	v_pk_mul_f32 v[94:95], v[24:25], v[60:61] op_sel:[0,1] op_sel_hi:[0,0] neg_hi:[1,0]
	v_pk_fma_f32 v[94:95], v[60:61], v[60:61], v[94:95] op_sel_hi:[0,1,1]
	ds_read_b64 v[26:27], v25 offset:52224
	ds_read_b64 v[28:29], v25 offset:56576
	ds_read_b64 v[30:31], v25 offset:60928
	ds_read_b64 v[58:59], v25 offset:65280
	s_waitcnt lgkmcnt(13)
	v_pk_mul_f32 v[96:97], v[4:5], v[94:95] op_sel:[1,1] op_sel_hi:[0,1] neg_lo:[0,1]
	v_pk_fma_f32 v[4:5], v[4:5], v[94:95], v[96:97] op_sel_hi:[1,0,1]
	v_pk_mul_f32 v[96:97], v[24:25], v[94:95] op_sel:[0,1] op_sel_hi:[0,0] neg_hi:[1,0]
	v_pk_fma_f32 v[94:95], v[60:61], v[94:95], v[96:97] op_sel_hi:[0,1,1]
	s_mov_b32 s35, s30
	s_waitcnt lgkmcnt(12)
	v_pk_mul_f32 v[96:97], v[6:7], v[94:95] op_sel:[1,1] op_sel_hi:[0,1] neg_lo:[0,1]
	v_pk_fma_f32 v[6:7], v[6:7], v[94:95], v[96:97] op_sel_hi:[1,0,1]
	v_pk_mul_f32 v[96:97], v[24:25], v[94:95] op_sel:[0,1] op_sel_hi:[0,0] neg_hi:[1,0]
	v_pk_fma_f32 v[94:95], v[60:61], v[94:95], v[96:97] op_sel_hi:[0,1,1]
	s_mov_b32 s26, s19
	s_waitcnt lgkmcnt(11)
	v_pk_mul_f32 v[96:97], v[8:9], v[94:95] op_sel:[1,1] op_sel_hi:[0,1] neg_lo:[0,1]
	v_pk_fma_f32 v[8:9], v[8:9], v[94:95], v[96:97] op_sel_hi:[1,0,1]
	v_pk_mul_f32 v[96:97], v[24:25], v[94:95] op_sel:[0,1] op_sel_hi:[0,0] neg_hi:[1,0]
	v_pk_fma_f32 v[94:95], v[60:61], v[94:95], v[96:97] op_sel_hi:[0,1,1]
	s_waitcnt lgkmcnt(0)
	v_pk_mul_f32 v[96:97], v[10:11], v[94:95] op_sel:[1,1] op_sel_hi:[0,1] neg_lo:[0,1]
	v_pk_fma_f32 v[10:11], v[10:11], v[94:95], v[96:97] op_sel_hi:[1,0,1]
	v_pk_mul_f32 v[96:97], v[24:25], v[94:95] op_sel:[0,1] op_sel_hi:[0,0] neg_hi:[1,0]
	v_pk_fma_f32 v[94:95], v[60:61], v[94:95], v[96:97] op_sel_hi:[0,1,1]
	s_barrier
	v_pk_mul_f32 v[96:97], v[12:13], v[94:95] op_sel:[1,1] op_sel_hi:[0,1] neg_lo:[0,1]
	v_pk_fma_f32 v[12:13], v[12:13], v[94:95], v[96:97] op_sel_hi:[1,0,1]
	v_pk_mul_f32 v[96:97], v[24:25], v[94:95] op_sel:[0,1] op_sel_hi:[0,0] neg_hi:[1,0]
	v_pk_fma_f32 v[94:95], v[60:61], v[94:95], v[96:97] op_sel_hi:[0,1,1]
	s_nop 0
	v_pk_mul_f32 v[96:97], v[14:15], v[94:95] op_sel:[1,1] op_sel_hi:[0,1] neg_lo:[0,1]
	v_pk_fma_f32 v[14:15], v[14:15], v[94:95], v[96:97] op_sel_hi:[1,0,1]
	v_pk_mul_f32 v[96:97], v[24:25], v[94:95] op_sel:[0,1] op_sel_hi:[0,0] neg_hi:[1,0]
	v_pk_fma_f32 v[94:95], v[60:61], v[94:95], v[96:97] op_sel_hi:[0,1,1]
	s_nop 0
	v_pk_mul_f32 v[96:97], v[16:17], v[94:95] op_sel:[1,1] op_sel_hi:[0,1] neg_lo:[0,1]
	v_pk_fma_f32 v[16:17], v[16:17], v[94:95], v[96:97] op_sel_hi:[1,0,1]
	v_pk_mul_f32 v[96:97], v[24:25], v[94:95] op_sel:[0,1] op_sel_hi:[0,0] neg_hi:[1,0]
	v_pk_fma_f32 v[94:95], v[60:61], v[94:95], v[96:97] op_sel_hi:[0,1,1]
	s_nop 0
	v_pk_mul_f32 v[96:97], v[18:19], v[94:95] op_sel:[1,1] op_sel_hi:[0,1] neg_lo:[0,1]
	v_pk_fma_f32 v[18:19], v[18:19], v[94:95], v[96:97] op_sel_hi:[1,0,1]
	v_pk_mul_f32 v[96:97], v[24:25], v[94:95] op_sel:[0,1] op_sel_hi:[0,0] neg_hi:[1,0]
	v_pk_fma_f32 v[94:95], v[60:61], v[94:95], v[96:97] op_sel_hi:[0,1,1]
	s_nop 0
	v_pk_mul_f32 v[96:97], v[20:21], v[94:95] op_sel:[1,1] op_sel_hi:[0,1] neg_lo:[0,1]
	v_pk_fma_f32 v[20:21], v[20:21], v[94:95], v[96:97] op_sel_hi:[1,0,1]
	v_pk_mul_f32 v[96:97], v[24:25], v[94:95] op_sel:[0,1] op_sel_hi:[0,0] neg_hi:[1,0]
	v_pk_fma_f32 v[94:95], v[60:61], v[94:95], v[96:97] op_sel_hi:[0,1,1]
	s_nop 0
	v_pk_mul_f32 v[96:97], v[22:23], v[94:95] op_sel:[1,1] op_sel_hi:[0,1] neg_lo:[0,1]
	v_pk_fma_f32 v[22:23], v[22:23], v[94:95], v[96:97] op_sel_hi:[1,0,1]
	v_pk_mul_f32 v[96:97], v[24:25], v[94:95] op_sel:[0,1] op_sel_hi:[0,0] neg_hi:[1,0]
	v_pk_fma_f32 v[94:95], v[60:61], v[94:95], v[96:97] op_sel_hi:[0,1,1]
	s_nop 0
	v_pk_mul_f32 v[96:97], v[26:27], v[94:95] op_sel:[1,1] op_sel_hi:[0,1] neg_lo:[0,1]
	v_pk_fma_f32 v[26:27], v[26:27], v[94:95], v[96:97] op_sel_hi:[1,0,1]
	v_pk_mul_f32 v[96:97], v[24:25], v[94:95] op_sel:[0,1] op_sel_hi:[0,0] neg_hi:[1,0]
	v_pk_fma_f32 v[94:95], v[60:61], v[94:95], v[96:97] op_sel_hi:[0,1,1]
	s_nop 0
	v_pk_mul_f32 v[96:97], v[28:29], v[94:95] op_sel:[1,1] op_sel_hi:[0,1] neg_lo:[0,1]
	v_pk_fma_f32 v[28:29], v[28:29], v[94:95], v[96:97] op_sel_hi:[1,0,1]
	v_pk_mul_f32 v[96:97], v[24:25], v[94:95] op_sel:[0,1] op_sel_hi:[0,0] neg_hi:[1,0]
	v_pk_fma_f32 v[94:95], v[60:61], v[94:95], v[96:97] op_sel_hi:[0,1,1]
	v_pk_mul_f32 v[24:25], v[24:25], v[94:95] op_sel:[0,1] op_sel_hi:[0,0] neg_hi:[1,0]
	v_pk_fma_f32 v[24:25], v[60:61], v[94:95], v[24:25] op_sel_hi:[0,1,1]
	v_pk_mul_f32 v[60:61], v[58:59], v[24:25] op_sel:[1,1] op_sel_hi:[0,1] neg_lo:[0,1]
	v_pk_fma_f32 v[24:25], v[58:59], v[24:25], v[60:61] op_sel_hi:[1,0,1]
	v_pk_add_f32 v[58:59], v[0:1], v[16:17]
	v_pk_add_f32 v[0:1], v[0:1], v[16:17] neg_lo:[0,1] neg_hi:[0,1]
	v_pk_add_f32 v[16:17], v[2:3], v[18:19]
	v_pk_add_f32 v[2:3], v[2:3], v[18:19] neg_lo:[0,1] neg_hi:[0,1]
	v_pk_mul_f32 v[96:97], v[30:31], v[94:95] op_sel:[1,1] op_sel_hi:[0,1] neg_lo:[0,1]
	v_pk_mul_f32 v[18:19], v[2:3], s[18:19]
	v_pk_fma_f32 v[30:31], v[30:31], v[94:95], v[96:97] op_sel_hi:[1,0,1]
	v_pk_fma_f32 v[2:3], v[2:3], s[30:31], v[18:19] op_sel:[0,0,1] op_sel_hi:[1,0,0]
	v_pk_add_f32 v[18:19], v[4:5], v[20:21]
	v_pk_add_f32 v[4:5], v[4:5], v[20:21] neg_lo:[0,1] neg_hi:[0,1]
	s_nop 0
	v_pk_mul_f32 v[20:21], v[4:5], s[10:11]
	s_nop 0
	v_pk_fma_f32 v[4:5], v[4:5], s[14:15], v[20:21] op_sel:[0,0,1] op_sel_hi:[1,0,0]
	v_pk_add_f32 v[20:21], v[6:7], v[22:23]
	v_pk_add_f32 v[6:7], v[6:7], v[22:23] neg_lo:[0,1] neg_hi:[0,1]
	s_nop 0
	v_pk_mul_f32 v[22:23], v[6:7], s[34:35]
	s_nop 0
	v_pk_fma_f32 v[6:7], v[6:7], s[26:27], v[22:23] op_sel:[0,0,1] op_sel_hi:[1,0,0]
	v_pk_add_f32 v[22:23], v[8:9], v[26:27]
	v_pk_add_f32 v[8:9], v[8:9], v[26:27] neg_lo:[0,1] neg_hi:[0,1]
	v_pk_add_f32 v[26:27], v[10:11], v[28:29]
	v_pk_add_f32 v[10:11], v[10:11], v[28:29] neg_lo:[0,1] neg_hi:[0,1]
	s_nop 0
	v_pk_mul_f32 v[28:29], v[10:11], s[34:35]
	s_nop 0
	v_pk_fma_f32 v[10:11], v[10:11], s[26:27], v[28:29] op_sel:[0,0,1] op_sel_hi:[1,0,0] neg_lo:[1,0,0] neg_hi:[1,0,0]
	v_pk_add_f32 v[28:29], v[12:13], v[30:31]
	v_pk_add_f32 v[12:13], v[12:13], v[30:31] neg_lo:[0,1] neg_hi:[0,1]
	s_nop 0
	v_pk_mul_f32 v[30:31], v[12:13], s[10:11]
	s_nop 0
	v_pk_fma_f32 v[12:13], v[12:13], s[14:15], v[30:31] op_sel:[0,0,1] op_sel_hi:[1,0,0] neg_lo:[1,0,0] neg_hi:[1,0,0]
	v_pk_add_f32 v[30:31], v[14:15], v[24:25]
	v_pk_add_f32 v[14:15], v[14:15], v[24:25] neg_lo:[0,1] neg_hi:[0,1]
	s_nop 0
	v_pk_mul_f32 v[24:25], v[14:15], s[18:19]
	s_nop 0
	v_pk_fma_f32 v[14:15], v[14:15], s[30:31], v[24:25] op_sel:[0,0,1] op_sel_hi:[1,0,0] neg_lo:[1,0,0] neg_hi:[1,0,0]
	v_pk_add_f32 v[24:25], v[58:59], v[22:23]
	v_pk_add_f32 v[22:23], v[58:59], v[22:23] neg_lo:[0,1] neg_hi:[0,1]
	v_pk_add_f32 v[58:59], v[16:17], v[26:27]
	v_pk_add_f32 v[16:17], v[16:17], v[26:27] neg_lo:[0,1] neg_hi:[0,1]
	s_nop 0
	v_pk_mul_f32 v[26:27], v[16:17], s[10:11]
	s_nop 0
	v_pk_fma_f32 v[16:17], v[16:17], s[14:15], v[26:27] op_sel:[0,0,1] op_sel_hi:[1,0,0]
	v_pk_add_f32 v[26:27], v[18:19], v[28:29]
	v_pk_add_f32 v[18:19], v[18:19], v[28:29] neg_lo:[0,1] neg_hi:[0,1]
	v_pk_add_f32 v[28:29], v[20:21], v[30:31]
	v_pk_add_f32 v[20:21], v[20:21], v[30:31] neg_lo:[0,1] neg_hi:[0,1]
	s_nop 0
	v_pk_mul_f32 v[30:31], v[20:21], s[10:11]
	s_nop 0
	v_pk_fma_f32 v[20:21], v[20:21], s[14:15], v[30:31] op_sel:[0,0,1] op_sel_hi:[1,0,0] neg_lo:[1,0,0] neg_hi:[1,0,0]
	v_pk_add_f32 v[30:31], v[0:1], v[8:9] op_sel:[0,1] op_sel_hi:[1,0] neg_hi:[0,1]
	v_pk_add_f32 v[0:1], v[0:1], v[8:9] op_sel:[0,1] op_sel_hi:[1,0] neg_lo:[0,1]
	v_pk_add_f32 v[8:9], v[2:3], v[10:11]
	v_pk_add_f32 v[2:3], v[2:3], v[10:11] neg_lo:[0,1] neg_hi:[0,1]
	s_nop 0
	v_pk_mul_f32 v[10:11], v[2:3], s[10:11]
	s_nop 0
	v_pk_fma_f32 v[2:3], v[2:3], s[14:15], v[10:11] op_sel:[0,0,1] op_sel_hi:[1,0,0]
	v_pk_add_f32 v[10:11], v[4:5], v[12:13]
	v_pk_add_f32 v[4:5], v[4:5], v[12:13] neg_lo:[0,1] neg_hi:[0,1]
	v_pk_add_f32 v[12:13], v[6:7], v[14:15]
	v_pk_add_f32 v[6:7], v[6:7], v[14:15] neg_lo:[0,1] neg_hi:[0,1]
	s_nop 0
	v_pk_mul_f32 v[14:15], v[6:7], s[10:11]
	s_nop 0
	v_pk_fma_f32 v[6:7], v[6:7], s[14:15], v[14:15] op_sel:[0,0,1] op_sel_hi:[1,0,0] neg_lo:[1,0,0] neg_hi:[1,0,0]
	v_pk_add_f32 v[14:15], v[24:25], v[26:27]
	v_pk_add_f32 v[24:25], v[24:25], v[26:27] neg_lo:[0,1] neg_hi:[0,1]
	v_pk_add_f32 v[26:27], v[58:59], v[28:29]
	v_pk_add_f32 v[28:29], v[58:59], v[28:29] neg_lo:[0,1] neg_hi:[0,1]
	v_pk_add_f32 v[58:59], v[22:23], v[18:19] op_sel:[0,1] op_sel_hi:[1,0] neg_hi:[0,1]
	v_pk_add_f32 v[18:19], v[22:23], v[18:19] op_sel:[0,1] op_sel_hi:[1,0] neg_lo:[0,1]
	v_pk_add_f32 v[22:23], v[16:17], v[20:21]
	v_pk_add_f32 v[16:17], v[16:17], v[20:21] neg_lo:[0,1] neg_hi:[0,1]
	v_pk_add_f32 v[20:21], v[30:31], v[10:11]
	v_pk_add_f32 v[10:11], v[30:31], v[10:11] neg_lo:[0,1] neg_hi:[0,1]
	v_pk_add_f32 v[30:31], v[8:9], v[12:13]
	v_pk_add_f32 v[8:9], v[8:9], v[12:13] neg_lo:[0,1] neg_hi:[0,1]
	v_pk_add_f32 v[12:13], v[0:1], v[4:5] op_sel:[0,1] op_sel_hi:[1,0] neg_hi:[0,1]
	v_pk_add_f32 v[0:1], v[0:1], v[4:5] op_sel:[0,1] op_sel_hi:[1,0] neg_lo:[0,1]
	v_pk_add_f32 v[4:5], v[2:3], v[6:7]
	v_pk_add_f32 v[2:3], v[2:3], v[6:7] neg_lo:[0,1] neg_hi:[0,1]
	s_nop 0
	v_pk_mul_f32 v[2:3], v[2:3], s[22:23]
	v_pk_add_f32 v[6:7], v[14:15], v[26:27]
	v_pk_add_f32 v[14:15], v[14:15], v[26:27] neg_lo:[0,1] neg_hi:[0,1]
	v_pk_add_f32 v[26:27], v[24:25], v[28:29] op_sel:[0,1] op_sel_hi:[1,0] neg_hi:[0,1]
	v_pk_add_f32 v[24:25], v[24:25], v[28:29] op_sel:[0,1] op_sel_hi:[1,0] neg_lo:[0,1]
	v_pk_add_f32 v[28:29], v[58:59], v[22:23]
	v_pk_add_f32 v[22:23], v[58:59], v[22:23] neg_lo:[0,1] neg_hi:[0,1]
	v_pk_add_f32 v[58:59], v[18:19], v[16:17] op_sel:[0,1] op_sel_hi:[1,0] neg_hi:[0,1]
	v_pk_add_f32 v[16:17], v[18:19], v[16:17] op_sel:[0,1] op_sel_hi:[1,0] neg_lo:[0,1]
	v_pk_add_f32 v[18:19], v[20:21], v[30:31]
	v_pk_add_f32 v[20:21], v[20:21], v[30:31] neg_lo:[0,1] neg_hi:[0,1]
	v_pk_add_f32 v[30:31], v[10:11], v[8:9] op_sel:[0,1] op_sel_hi:[1,0] neg_hi:[0,1]
	v_pk_add_f32 v[8:9], v[10:11], v[8:9] op_sel:[0,1] op_sel_hi:[1,0] neg_lo:[0,1]
	v_pk_add_f32 v[10:11], v[12:13], v[4:5]
	v_pk_add_f32 v[4:5], v[12:13], v[4:5] neg_lo:[0,1] neg_hi:[0,1]
	v_pk_add_f32 v[12:13], v[0:1], v[2:3] op_sel:[0,1] op_sel_hi:[1,0]
	v_pk_add_f32 v[0:1], v[0:1], v[2:3] op_sel:[0,1] op_sel_hi:[1,0] neg_lo:[0,1] neg_hi:[0,1]
	v_lshlrev_b32_e32 v2, 4, v41
	v_and_or_b32 v2, v2, s7, v98
	v_ashrrev_i32_e32 v3, 4, v2
	v_lshlrev_b32_e32 v3, 3, v3
	v_lshlrev_b32_e32 v2, 3, v2
	v_add3_u32 v2, 0, v3, v2
	v_add_u32_e32 v3, 0x800, v2
	v_mov_b32_e32 v41, v32
	ds_write2_b64 v2, v[6:7], v[18:19] offset1:34
	ds_write2_b64 v3, v[14:15], v[20:21] offset0:16 offset1:50
	ds_write2_b64 v2, v[26:27], v[30:31] offset0:136 offset1:170
	ds_write2_b64 v3, v[24:25], v[8:9] offset0:152 offset1:186
	ds_write2_b64 v2, v[28:29], v[10:11] offset0:68 offset1:102
	ds_write2_b64 v3, v[22:23], v[4:5] offset0:84 offset1:118
	ds_write2_b64 v2, v[58:59], v[12:13] offset0:204 offset1:238
	ds_write2_b64 v3, v[16:17], v[0:1] offset0:220 offset1:254
	s_waitcnt lgkmcnt(0)
	s_barrier
	s_nop 0
	v_and_b32_e32 v98, 0x1ff, v41
	v_cvt_f32_u32_e32 v24, v98
	v_ashrrev_i32_e32 v0, 4, v41
	v_lshlrev_b32_e32 v0, 3, v0
	v_lshlrev_b32_e32 v1, 3, v41
	v_mul_f32_e32 v60, 0x39000000, v24
	v_sin_f32_e32 v24, v60
	v_cos_f32_e32 v60, v60
	v_add3_u32 v25, 0, v0, v1
	ds_read_b64 v[0:1], v25
	ds_read_b64 v[2:3], v25 offset:4352
	ds_read_b64 v[4:5], v25 offset:8704
	ds_read_b64 v[6:7], v25 offset:13056
	ds_read_b64 v[8:9], v25 offset:17408
	ds_read_b64 v[10:11], v25 offset:21760
	ds_read_b64 v[12:13], v25 offset:26112
	ds_read_b64 v[14:15], v25 offset:30464
	v_xor_b32_e32 v61, 0x80000000, v24
	s_waitcnt lgkmcnt(6)
	v_pk_mul_f32 v[94:95], v[2:3], v[24:25] op_sel:[1,0] op_sel_hi:[0,0] neg_hi:[0,1]
	v_pk_fma_f32 v[2:3], v[2:3], v[60:61], v[94:95] op_sel_hi:[1,0,1]
	v_pk_mul_f32 v[94:95], v[24:25], v[60:61] op_sel:[0,1] op_sel_hi:[0,0] neg_hi:[1,0]
	v_pk_fma_f32 v[94:95], v[60:61], v[60:61], v[94:95] op_sel_hi:[0,1,1]
	ds_read_b64 v[16:17], v25 offset:34816
	ds_read_b64 v[18:19], v25 offset:39168
	ds_read_b64 v[20:21], v25 offset:43520
	ds_read_b64 v[22:23], v25 offset:47872
	s_waitcnt lgkmcnt(9)
	v_pk_mul_f32 v[96:97], v[4:5], v[94:95] op_sel:[1,1] op_sel_hi:[0,1] neg_lo:[0,1]
	v_pk_fma_f32 v[4:5], v[4:5], v[94:95], v[96:97] op_sel_hi:[1,0,1]
	v_pk_mul_f32 v[96:97], v[24:25], v[94:95] op_sel:[0,1] op_sel_hi:[0,0] neg_hi:[1,0]
	v_pk_fma_f32 v[94:95], v[60:61], v[94:95], v[96:97] op_sel_hi:[0,1,1]
	ds_read_b64 v[26:27], v25 offset:52224
	ds_read_b64 v[28:29], v25 offset:56576
	ds_read_b64 v[30:31], v25 offset:60928
	ds_read_b64 v[58:59], v25 offset:65280
	s_waitcnt lgkmcnt(12)
	v_pk_mul_f32 v[96:97], v[6:7], v[94:95] op_sel:[1,1] op_sel_hi:[0,1] neg_lo:[0,1]
	v_pk_fma_f32 v[6:7], v[6:7], v[94:95], v[96:97] op_sel_hi:[1,0,1]
	v_pk_mul_f32 v[96:97], v[24:25], v[94:95] op_sel:[0,1] op_sel_hi:[0,0] neg_hi:[1,0]
	v_pk_fma_f32 v[94:95], v[60:61], v[94:95], v[96:97] op_sel_hi:[0,1,1]
	s_waitcnt lgkmcnt(0)
	v_pk_mul_f32 v[96:97], v[8:9], v[94:95] op_sel:[1,1] op_sel_hi:[0,1] neg_lo:[0,1]
	v_pk_fma_f32 v[8:9], v[8:9], v[94:95], v[96:97] op_sel_hi:[1,0,1]
	v_pk_mul_f32 v[96:97], v[24:25], v[94:95] op_sel:[0,1] op_sel_hi:[0,0] neg_hi:[1,0]
	v_pk_fma_f32 v[94:95], v[60:61], v[94:95], v[96:97] op_sel_hi:[0,1,1]
	s_barrier
	v_pk_mul_f32 v[96:97], v[10:11], v[94:95] op_sel:[1,1] op_sel_hi:[0,1] neg_lo:[0,1]
	v_pk_fma_f32 v[10:11], v[10:11], v[94:95], v[96:97] op_sel_hi:[1,0,1]
	v_pk_mul_f32 v[96:97], v[24:25], v[94:95] op_sel:[0,1] op_sel_hi:[0,0] neg_hi:[1,0]
	v_pk_fma_f32 v[94:95], v[60:61], v[94:95], v[96:97] op_sel_hi:[0,1,1]
	s_nop 0
	v_pk_mul_f32 v[96:97], v[12:13], v[94:95] op_sel:[1,1] op_sel_hi:[0,1] neg_lo:[0,1]
	v_pk_fma_f32 v[12:13], v[12:13], v[94:95], v[96:97] op_sel_hi:[1,0,1]
	v_pk_mul_f32 v[96:97], v[24:25], v[94:95] op_sel:[0,1] op_sel_hi:[0,0] neg_hi:[1,0]
	v_pk_fma_f32 v[94:95], v[60:61], v[94:95], v[96:97] op_sel_hi:[0,1,1]
	s_nop 0
	v_pk_mul_f32 v[96:97], v[14:15], v[94:95] op_sel:[1,1] op_sel_hi:[0,1] neg_lo:[0,1]
	v_pk_fma_f32 v[14:15], v[14:15], v[94:95], v[96:97] op_sel_hi:[1,0,1]
	v_pk_mul_f32 v[96:97], v[24:25], v[94:95] op_sel:[0,1] op_sel_hi:[0,0] neg_hi:[1,0]
	v_pk_fma_f32 v[94:95], v[60:61], v[94:95], v[96:97] op_sel_hi:[0,1,1]
	s_nop 0
	v_pk_mul_f32 v[96:97], v[16:17], v[94:95] op_sel:[1,1] op_sel_hi:[0,1] neg_lo:[0,1]
	v_pk_fma_f32 v[16:17], v[16:17], v[94:95], v[96:97] op_sel_hi:[1,0,1]
	v_pk_mul_f32 v[96:97], v[24:25], v[94:95] op_sel:[0,1] op_sel_hi:[0,0] neg_hi:[1,0]
	v_pk_fma_f32 v[94:95], v[60:61], v[94:95], v[96:97] op_sel_hi:[0,1,1]
	s_nop 0
	v_pk_mul_f32 v[96:97], v[18:19], v[94:95] op_sel:[1,1] op_sel_hi:[0,1] neg_lo:[0,1]
	v_pk_fma_f32 v[18:19], v[18:19], v[94:95], v[96:97] op_sel_hi:[1,0,1]
	v_pk_mul_f32 v[96:97], v[24:25], v[94:95] op_sel:[0,1] op_sel_hi:[0,0] neg_hi:[1,0]
	v_pk_fma_f32 v[94:95], v[60:61], v[94:95], v[96:97] op_sel_hi:[0,1,1]
	s_nop 0
	v_pk_mul_f32 v[96:97], v[20:21], v[94:95] op_sel:[1,1] op_sel_hi:[0,1] neg_lo:[0,1]
	v_pk_fma_f32 v[20:21], v[20:21], v[94:95], v[96:97] op_sel_hi:[1,0,1]
	v_pk_mul_f32 v[96:97], v[24:25], v[94:95] op_sel:[0,1] op_sel_hi:[0,0] neg_hi:[1,0]
	v_pk_fma_f32 v[94:95], v[60:61], v[94:95], v[96:97] op_sel_hi:[0,1,1]
	s_nop 0
	v_pk_mul_f32 v[96:97], v[22:23], v[94:95] op_sel:[1,1] op_sel_hi:[0,1] neg_lo:[0,1]
	v_pk_fma_f32 v[22:23], v[22:23], v[94:95], v[96:97] op_sel_hi:[1,0,1]
	v_pk_mul_f32 v[96:97], v[24:25], v[94:95] op_sel:[0,1] op_sel_hi:[0,0] neg_hi:[1,0]
	v_pk_fma_f32 v[94:95], v[60:61], v[94:95], v[96:97] op_sel_hi:[0,1,1]
	s_nop 0
	v_pk_mul_f32 v[96:97], v[26:27], v[94:95] op_sel:[1,1] op_sel_hi:[0,1] neg_lo:[0,1]
	v_pk_fma_f32 v[26:27], v[26:27], v[94:95], v[96:97] op_sel_hi:[1,0,1]
	v_pk_mul_f32 v[96:97], v[24:25], v[94:95] op_sel:[0,1] op_sel_hi:[0,0] neg_hi:[1,0]
	v_pk_fma_f32 v[94:95], v[60:61], v[94:95], v[96:97] op_sel_hi:[0,1,1]
	s_nop 0
	v_pk_mul_f32 v[96:97], v[28:29], v[94:95] op_sel:[1,1] op_sel_hi:[0,1] neg_lo:[0,1]
	v_pk_fma_f32 v[28:29], v[28:29], v[94:95], v[96:97] op_sel_hi:[1,0,1]
	v_pk_mul_f32 v[96:97], v[24:25], v[94:95] op_sel:[0,1] op_sel_hi:[0,0] neg_hi:[1,0]
	v_pk_fma_f32 v[94:95], v[60:61], v[94:95], v[96:97] op_sel_hi:[0,1,1]
	v_pk_mul_f32 v[24:25], v[24:25], v[94:95] op_sel:[0,1] op_sel_hi:[0,0] neg_hi:[1,0]
	v_pk_fma_f32 v[24:25], v[60:61], v[94:95], v[24:25] op_sel_hi:[0,1,1]
	v_pk_mul_f32 v[60:61], v[58:59], v[24:25] op_sel:[1,1] op_sel_hi:[0,1] neg_lo:[0,1]
	v_pk_fma_f32 v[24:25], v[58:59], v[24:25], v[60:61] op_sel_hi:[1,0,1]
	v_pk_add_f32 v[58:59], v[0:1], v[16:17]
	v_pk_add_f32 v[0:1], v[0:1], v[16:17] neg_lo:[0,1] neg_hi:[0,1]
	v_pk_add_f32 v[16:17], v[2:3], v[18:19]
	v_pk_add_f32 v[2:3], v[2:3], v[18:19] neg_lo:[0,1] neg_hi:[0,1]
	v_pk_mul_f32 v[96:97], v[30:31], v[94:95] op_sel:[1,1] op_sel_hi:[0,1] neg_lo:[0,1]
	v_pk_mul_f32 v[18:19], v[2:3], s[18:19]
	v_pk_fma_f32 v[30:31], v[30:31], v[94:95], v[96:97] op_sel_hi:[1,0,1]
	v_pk_fma_f32 v[2:3], v[2:3], s[30:31], v[18:19] op_sel:[0,0,1] op_sel_hi:[1,0,0]
	v_pk_add_f32 v[18:19], v[4:5], v[20:21]
	v_pk_add_f32 v[4:5], v[4:5], v[20:21] neg_lo:[0,1] neg_hi:[0,1]
	s_nop 0
	v_pk_mul_f32 v[20:21], v[4:5], s[10:11]
	s_nop 0
	v_pk_fma_f32 v[4:5], v[4:5], s[14:15], v[20:21] op_sel:[0,0,1] op_sel_hi:[1,0,0]
	v_pk_add_f32 v[20:21], v[6:7], v[22:23]
	v_pk_add_f32 v[6:7], v[6:7], v[22:23] neg_lo:[0,1] neg_hi:[0,1]
	s_nop 0
	v_pk_mul_f32 v[22:23], v[6:7], s[34:35]
	s_nop 0
	v_pk_fma_f32 v[6:7], v[6:7], s[26:27], v[22:23] op_sel:[0,0,1] op_sel_hi:[1,0,0]
	v_pk_add_f32 v[22:23], v[8:9], v[26:27]
	v_pk_add_f32 v[8:9], v[8:9], v[26:27] neg_lo:[0,1] neg_hi:[0,1]
	v_pk_add_f32 v[26:27], v[10:11], v[28:29]
	v_pk_add_f32 v[10:11], v[10:11], v[28:29] neg_lo:[0,1] neg_hi:[0,1]
	s_nop 0
	v_pk_mul_f32 v[28:29], v[10:11], s[34:35]
	s_nop 0
	v_pk_fma_f32 v[10:11], v[10:11], s[26:27], v[28:29] op_sel:[0,0,1] op_sel_hi:[1,0,0] neg_lo:[1,0,0] neg_hi:[1,0,0]
	v_pk_add_f32 v[28:29], v[12:13], v[30:31]
	v_pk_add_f32 v[12:13], v[12:13], v[30:31] neg_lo:[0,1] neg_hi:[0,1]
	s_nop 0
	v_pk_mul_f32 v[30:31], v[12:13], s[10:11]
	s_nop 0
	v_pk_fma_f32 v[12:13], v[12:13], s[14:15], v[30:31] op_sel:[0,0,1] op_sel_hi:[1,0,0] neg_lo:[1,0,0] neg_hi:[1,0,0]
	v_pk_add_f32 v[30:31], v[14:15], v[24:25]
	v_pk_add_f32 v[14:15], v[14:15], v[24:25] neg_lo:[0,1] neg_hi:[0,1]
	s_nop 0
	v_pk_mul_f32 v[24:25], v[14:15], s[18:19]
	s_nop 0
	v_pk_fma_f32 v[14:15], v[14:15], s[30:31], v[24:25] op_sel:[0,0,1] op_sel_hi:[1,0,0] neg_lo:[1,0,0] neg_hi:[1,0,0]
	v_pk_add_f32 v[24:25], v[58:59], v[22:23]
	v_pk_add_f32 v[22:23], v[58:59], v[22:23] neg_lo:[0,1] neg_hi:[0,1]
	v_pk_add_f32 v[58:59], v[16:17], v[26:27]
	v_pk_add_f32 v[16:17], v[16:17], v[26:27] neg_lo:[0,1] neg_hi:[0,1]
	s_nop 0
	v_pk_mul_f32 v[26:27], v[16:17], s[10:11]
	s_nop 0
	v_pk_fma_f32 v[16:17], v[16:17], s[14:15], v[26:27] op_sel:[0,0,1] op_sel_hi:[1,0,0]
	v_pk_add_f32 v[26:27], v[18:19], v[28:29]
	v_pk_add_f32 v[18:19], v[18:19], v[28:29] neg_lo:[0,1] neg_hi:[0,1]
	v_pk_add_f32 v[28:29], v[20:21], v[30:31]
	v_pk_add_f32 v[20:21], v[20:21], v[30:31] neg_lo:[0,1] neg_hi:[0,1]
	s_nop 0
	v_pk_mul_f32 v[30:31], v[20:21], s[10:11]
	s_nop 0
	v_pk_fma_f32 v[20:21], v[20:21], s[14:15], v[30:31] op_sel:[0,0,1] op_sel_hi:[1,0,0] neg_lo:[1,0,0] neg_hi:[1,0,0]
	v_pk_add_f32 v[30:31], v[0:1], v[8:9] op_sel:[0,1] op_sel_hi:[1,0] neg_hi:[0,1]
	v_pk_add_f32 v[0:1], v[0:1], v[8:9] op_sel:[0,1] op_sel_hi:[1,0] neg_lo:[0,1]
	v_pk_add_f32 v[8:9], v[2:3], v[10:11]
	v_pk_add_f32 v[2:3], v[2:3], v[10:11] neg_lo:[0,1] neg_hi:[0,1]
	s_nop 0
	v_pk_mul_f32 v[10:11], v[2:3], s[10:11]
	s_nop 0
	v_pk_fma_f32 v[2:3], v[2:3], s[14:15], v[10:11] op_sel:[0,0,1] op_sel_hi:[1,0,0]
	v_pk_add_f32 v[10:11], v[4:5], v[12:13]
	v_pk_add_f32 v[4:5], v[4:5], v[12:13] neg_lo:[0,1] neg_hi:[0,1]
	v_pk_add_f32 v[12:13], v[6:7], v[14:15]
	v_pk_add_f32 v[6:7], v[6:7], v[14:15] neg_lo:[0,1] neg_hi:[0,1]
	s_nop 0
	v_pk_mul_f32 v[14:15], v[6:7], s[10:11]
	s_nop 0
	v_pk_fma_f32 v[6:7], v[6:7], s[14:15], v[14:15] op_sel:[0,0,1] op_sel_hi:[1,0,0] neg_lo:[1,0,0] neg_hi:[1,0,0]
	v_pk_add_f32 v[14:15], v[24:25], v[26:27]
	v_pk_add_f32 v[24:25], v[24:25], v[26:27] neg_lo:[0,1] neg_hi:[0,1]
	v_pk_add_f32 v[26:27], v[58:59], v[28:29]
	v_pk_add_f32 v[28:29], v[58:59], v[28:29] neg_lo:[0,1] neg_hi:[0,1]
	v_pk_add_f32 v[58:59], v[22:23], v[18:19] op_sel:[0,1] op_sel_hi:[1,0] neg_hi:[0,1]
	v_pk_add_f32 v[18:19], v[22:23], v[18:19] op_sel:[0,1] op_sel_hi:[1,0] neg_lo:[0,1]
	v_pk_add_f32 v[22:23], v[16:17], v[20:21]
	v_pk_add_f32 v[16:17], v[16:17], v[20:21] neg_lo:[0,1] neg_hi:[0,1]
	v_pk_add_f32 v[20:21], v[30:31], v[10:11]
	v_pk_add_f32 v[10:11], v[30:31], v[10:11] neg_lo:[0,1] neg_hi:[0,1]
	v_pk_add_f32 v[30:31], v[8:9], v[12:13]
	v_pk_add_f32 v[8:9], v[8:9], v[12:13] neg_lo:[0,1] neg_hi:[0,1]
	v_pk_add_f32 v[12:13], v[0:1], v[4:5] op_sel:[0,1] op_sel_hi:[1,0] neg_hi:[0,1]
	v_pk_add_f32 v[0:1], v[0:1], v[4:5] op_sel:[0,1] op_sel_hi:[1,0] neg_lo:[0,1]
	v_pk_add_f32 v[4:5], v[2:3], v[6:7]
	v_pk_add_f32 v[2:3], v[2:3], v[6:7] neg_lo:[0,1] neg_hi:[0,1]
	s_nop 0
	v_pk_mul_f32 v[2:3], v[2:3], s[22:23]
	v_pk_add_f32 v[6:7], v[14:15], v[26:27]
	v_pk_add_f32 v[14:15], v[14:15], v[26:27] neg_lo:[0,1] neg_hi:[0,1]
	v_pk_add_f32 v[26:27], v[24:25], v[28:29] op_sel:[0,1] op_sel_hi:[1,0] neg_hi:[0,1]
	v_pk_add_f32 v[24:25], v[24:25], v[28:29] op_sel:[0,1] op_sel_hi:[1,0] neg_lo:[0,1]
	v_pk_add_f32 v[28:29], v[58:59], v[22:23]
	v_pk_add_f32 v[22:23], v[58:59], v[22:23] neg_lo:[0,1] neg_hi:[0,1]
	v_pk_add_f32 v[58:59], v[18:19], v[16:17] op_sel:[0,1] op_sel_hi:[1,0] neg_hi:[0,1]
	v_pk_add_f32 v[16:17], v[18:19], v[16:17] op_sel:[0,1] op_sel_hi:[1,0] neg_lo:[0,1]
	v_pk_add_f32 v[18:19], v[20:21], v[30:31]
	v_pk_add_f32 v[20:21], v[20:21], v[30:31] neg_lo:[0,1] neg_hi:[0,1]
	v_pk_add_f32 v[30:31], v[10:11], v[8:9] op_sel:[0,1] op_sel_hi:[1,0] neg_hi:[0,1]
	v_pk_add_f32 v[8:9], v[10:11], v[8:9] op_sel:[0,1] op_sel_hi:[1,0] neg_lo:[0,1]
	v_pk_add_f32 v[10:11], v[12:13], v[4:5]
	v_pk_add_f32 v[4:5], v[12:13], v[4:5] neg_lo:[0,1] neg_hi:[0,1]
	v_pk_add_f32 v[12:13], v[0:1], v[2:3] op_sel:[0,1] op_sel_hi:[1,0]
	v_pk_add_f32 v[0:1], v[0:1], v[2:3] op_sel:[0,1] op_sel_hi:[1,0] neg_lo:[0,1] neg_hi:[0,1]
	v_lshlrev_b32_e32 v2, 4, v41
	v_and_or_b32 v2, v2, s15, v98
	v_ashrrev_i32_e32 v3, 4, v2
	v_lshlrev_b32_e32 v3, 3, v3
	v_lshlrev_b32_e32 v2, 3, v2
	v_add3_u32 v2, 0, v3, v2
	ds_write_b64 v2, v[6:7]
	ds_write_b64 v2, v[14:15] offset:34816
	ds_write_b64 v2, v[26:27] offset:17408
	ds_write_b64 v2, v[24:25] offset:52224
	ds_write_b64 v2, v[28:29] offset:8704
	ds_write_b64 v2, v[22:23] offset:43520
	ds_write_b64 v2, v[58:59] offset:26112
	ds_write_b64 v2, v[16:17] offset:60928
	ds_write_b64 v2, v[18:19] offset:4352
	ds_write_b64 v2, v[20:21] offset:39168
	ds_write_b64 v2, v[30:31] offset:21760
	ds_write_b64 v2, v[8:9] offset:56576
	ds_write_b64 v2, v[10:11] offset:13056
	ds_write_b64 v2, v[4:5] offset:47872
	ds_write_b64 v2, v[12:13] offset:30464
	ds_write_b64 v2, v[0:1] offset:65280
	s_waitcnt lgkmcnt(0)
	s_barrier
	s_and_saveexec_b64 s[28:29], s[40:41]
	s_cbranch_execz .LBB0_602
	s_add_u32 s4, s38, 0x800000
	s_addc_u32 s5, s39, 0
	v_lshl_add_u64 v[0:1], v[48:49], 1, s[4:5]
	global_load_dwordx4 v[8:11], v[0:1], off offset:16
	global_load_dwordx4 v[12:15], v[0:1], off
	v_mov_b32_e32 v19, 0
	v_mov_b32_e32 v21, 0
	v_mov_b32_e32 v157, 0
	s_and_saveexec_b64 s[8:9], s[42:43]
	s_cbranch_execz .LBB0_678
	v_lshl_add_u64 v[2:3], v[172:173], 1, s[4:5]
	global_load_ushort v157, v[2:3], off offset:-2
